# v35 + P3 comb items: all 24 loads of a half hoisted ahead of the 8 compute+store steps (de-serialised load/wait/store ladder)
# speedup vs baseline: 1.0124x; 1.0124x over previous
.LBB0_938:
	v_readlane_b32 s2, v236, 63
	s_cmp_lg_u32 s2, -1
	s_cselect_b32 s2, s2, 0
	s_cselect_b32 s3, s9, 0
	v_mov_b32_e32 v2, s2
	v_mov_b32_e32 v3, s3
	s_waitcnt lgkmcnt(0)
	s_barrier
	flat_load_dword v0, v[2:3] sc0 sc1
	s_waitcnt vmcnt(0)
	v_readlane_b32 s2, v236, 61
	s_waitcnt lgkmcnt(0)
	s_nop 0
	v_add_u32_e32 v2, s2, v0
	s_movk_i32 s2, 0x1ba4
	v_cmp_gt_i32_e32 vcc, s2, v2
	s_mov_b64 s[2:3], -1
	s_and_saveexec_b64 s[44:45], vcc
	s_cbranch_execz .LBB0_933
	v_cmp_lt_i32_e32 vcc, 35, v2
	s_and_saveexec_b64 s[2:3], vcc
	s_xor_b64 s[46:47], exec, s[2:3]
	s_cbranch_execz .LBB0_983
	s_movk_i32 s2, 0xa23
	v_cmp_lt_u32_e32 vcc, s2, v2
	s_and_saveexec_b64 s[2:3], vcc
	s_xor_b64 s[48:49], exec, s[2:3]
	s_cbranch_execz .LBB0_974
	s_movk_i32 s2, 0xf23
	v_cmp_lt_u32_e32 vcc, s2, v2
	s_and_saveexec_b64 s[2:3], vcc
	s_xor_b64 s[4:5], exec, s[2:3]
	s_cbranch_execz .LBB0_947
	s_movk_i32 s2, 0x1923
	v_cmp_lt_u32_e32 vcc, s2, v2
	s_and_saveexec_b64 s[2:3], vcc
	s_xor_b64 s[2:3], exec, s[2:3]
	s_cbranch_execz .LBB0_944
	v_mbcnt_lo_u32_b32 v0, -1, 0
	v_mbcnt_hi_u32_b32 v0, -1, v0
	v_mov_b64_e32 v[4:5], s[14:15]
	v_or_b32_e32 v6, s8, v0
	v_lshl_add_u32 v0, v2, 7, v159
	v_ashrrev_i32_e32 v2, 1, v6
	v_ashrrev_i32_e32 v3, 31, v2
	v_lshl_add_u64 v[2:3], v[2:3], 0, v[0:1]
	v_mad_u64_u32 v[10:11], s[6:7], v2, s52, v[4:5]
	v_lshlrev_b32_e32 v0, 1, v6
	v_mad_i32_i24 v11, v3, s52, v11
	v_and_b32_e32 v19, 2, v0
	v_lshl_add_u64 v[2:3], v[2:3], 4, s[16:17]
	s_mov_b64 s[6:7], 0x140000
	v_lshl_add_u64 v[14:15], v[2:3], 0, s[6:7]
	s_mov_b64 s[6:7], 0x280000
	v_lshlrev_b32_e32 v0, 2, v19
	v_lshl_add_u64 v[12:13], v[2:3], 0, s[6:7]
	v_lshl_add_u64 v[16:17], v[2:3], 0, v[0:1]
	v_lshl_add_u64 v[2:3], v[14:15], 0, v[0:1]
	global_load_dword v4, v[16:17], off
	global_load_dword v5, v[2:3], off
	v_lshl_add_u64 v[2:3], v[12:13], 0, v[0:1]
	global_load_dword v0, v[2:3], off
	s_waitcnt vmcnt(0) lgkmcnt(0)
	v_max3_f32 v2, v4, v5, v0
	v_sub_f32_e32 v3, v4, v2
	v_mul_f32_e32 v3, 0x3fb8aa3b, v3
	v_exp_f32_e32 v23, v3
	v_sub_f32_e32 v3, v5, v2
	v_mul_f32_e32 v3, 0x3fb8aa3b, v3
	v_sub_f32_e32 v0, v0, v2
	v_exp_f32_e32 v22, v3
	v_mul_f32_e32 v0, 0x3fb8aa3b, v0
	v_exp_f32_e32 v0, v0
	v_add_f32_e32 v2, v23, v22
	v_add_f32_e32 v2, v0, v2
	v_div_scale_f32 v3, s[6:7], v2, v2, 1.0
	v_rcp_f32_e32 v4, v3
	s_nop 0
	v_fma_f32 v5, -v3, v4, 1.0
	v_fmac_f32_e32 v4, v5, v4
	v_div_scale_f32 v5, vcc, 1.0, v2, 1.0
	v_mul_f32_e32 v6, v5, v4
	v_fma_f32 v7, -v3, v6, v5
	v_fmac_f32_e32 v6, v7, v4
	v_fma_f32 v3, -v3, v6, v5
	v_div_fmas_f32 v3, v3, v4, v6
	v_div_fixup_f32 v30, v3, v2, 1.0
	v_mul_f32_e32 v18, v0, v30
	v_lshlrev_b32_e32 v0, 7, v19
	v_lshl_add_u64 v[20:21], v[10:11], 0, v[0:1]
	global_load_dwordx4 v[40:43], v[20:21], off offset:2560
	global_load_dwordx4 v[44:47], v[20:21], off offset:3584
	v_add_co_u32_e32 v24, vcc, s53, v20
	v_pk_mul_f32 v[22:23], v[22:23], v[30:31] op_sel_hi:[1,0]
	s_nop 0
	v_addc_co_u32_e32 v25, vcc, 0, v21, vcc
	global_load_dwordx4 v[48:51], v[24:25], off
	global_load_dwordx4 v[52:55], v[20:21], off offset:2576
	s_nop 0
	global_load_dwordx4 v[56:59], v[20:21], off offset:3600
	global_load_dwordx4 v[60:63], v[24:25], off offset:16
	global_load_dwordx4 v[64:67], v[20:21], off offset:2592
	s_nop 0
	global_load_dwordx4 v[68:71], v[20:21], off offset:3616
	global_load_dwordx4 v[72:75], v[24:25], off offset:32
	global_load_dwordx4 v[76:79], v[20:21], off offset:2608
	s_nop 0
	global_load_dwordx4 v[80:83], v[20:21], off offset:3632
	global_load_dwordx4 v[84:87], v[24:25], off offset:48
	global_load_dwordx4 v[88:91], v[20:21], off offset:2624
	s_nop 0
	global_load_dwordx4 v[92:95], v[20:21], off offset:3648
	global_load_dwordx4 v[96:99], v[24:25], off offset:64
	global_load_dwordx4 v[100:103], v[20:21], off offset:2640
	s_nop 0
	global_load_dwordx4 v[104:107], v[20:21], off offset:3664
	global_load_dwordx4 v[108:111], v[24:25], off offset:80
	global_load_dwordx4 v[112:115], v[20:21], off offset:2656
	s_nop 0
	global_load_dwordx4 v[116:119], v[20:21], off offset:3680
	global_load_dwordx4 v[124:127], v[24:25], off offset:96
	global_load_dwordx4 v[128:131], v[20:21], off offset:2672
	s_nop 0
	global_load_dwordx4 v[132:135], v[20:21], off offset:3696
	s_nop 0
	global_load_dwordx4 v[136:139], v[24:25], off offset:112
	s_waitcnt vmcnt(0) lgkmcnt(0)
	v_lshlrev_b32_e32 v36, 16, v40
	v_and_b32_e32 v37, 0xffff0000, v44
	v_lshlrev_b32_e32 v30, 16, v44
	v_and_b32_e32 v31, 0xffff0000, v40
	v_pk_mul_f32 v[36:37], v[22:23], v[36:37] op_sel:[1,0] op_sel_hi:[0,1]
	v_pk_fma_f32 v[30:31], v[22:23], v[30:31], v[36:37]
	v_lshlrev_b32_e32 v6, 16, v41
	v_lshlrev_b32_e32 v32, 16, v48
	v_and_b32_e32 v33, 0xffff0000, v48
	v_pk_fma_f32 v[30:31], v[18:19], v[32:33], v[30:31] op_sel_hi:[0,1,1]
	v_cvt_pk_bf16_f32 v2, v30, v31
	v_lshlrev_b32_e32 v30, 16, v45
	v_and_b32_e32 v7, 0xffff0000, v45
	v_and_b32_e32 v31, 0xffff0000, v41
	v_pk_mul_f32 v[6:7], v[22:23], v[6:7] op_sel:[1,0] op_sel_hi:[0,1]
	v_lshlrev_b32_e32 v26, 16, v49
	v_and_b32_e32 v27, 0xffff0000, v49
	v_pk_fma_f32 v[6:7], v[22:23], v[30:31], v[6:7]
	v_lshlrev_b32_e32 v34, 16, v50
	v_pk_fma_f32 v[6:7], v[18:19], v[26:27], v[6:7] op_sel_hi:[0,1,1]
	v_lshlrev_b32_e32 v26, 16, v42
	v_and_b32_e32 v27, 0xffff0000, v46
	v_cvt_pk_bf16_f32 v3, v6, v7
	v_lshlrev_b32_e32 v6, 16, v46
	v_and_b32_e32 v7, 0xffff0000, v42
	v_pk_mul_f32 v[26:27], v[22:23], v[26:27] op_sel:[1,0] op_sel_hi:[0,1]
	v_and_b32_e32 v35, 0xffff0000, v50
	v_pk_fma_f32 v[6:7], v[22:23], v[6:7], v[26:27]
	v_lshlrev_b32_e32 v8, 16, v43
	v_pk_fma_f32 v[6:7], v[18:19], v[34:35], v[6:7] op_sel_hi:[0,1,1]
	v_cvt_pk_bf16_f32 v4, v6, v7
	v_lshlrev_b32_e32 v6, 16, v47
	v_and_b32_e32 v9, 0xffff0000, v47
	v_and_b32_e32 v7, 0xffff0000, v43
	v_pk_mul_f32 v[8:9], v[22:23], v[8:9] op_sel:[1,0] op_sel_hi:[0,1]
	v_lshlrev_b32_e32 v28, 16, v51
	v_and_b32_e32 v29, 0xffff0000, v51
	v_pk_fma_f32 v[6:7], v[22:23], v[6:7], v[8:9]
	s_nop 0
	v_pk_fma_f32 v[6:7], v[18:19], v[28:29], v[6:7] op_sel_hi:[0,1,1]
	v_cvt_pk_bf16_f32 v5, v6, v7
	global_store_dwordx4 v[20:21], v[2:5], off offset:2560
	v_lshlrev_b32_e32 v34, 16, v52
	v_and_b32_e32 v35, 0xffff0000, v56
	v_lshlrev_b32_e32 v32, 16, v56
	v_and_b32_e32 v33, 0xffff0000, v52
	v_pk_mul_f32 v[34:35], v[22:23], v[34:35] op_sel:[1,0] op_sel_hi:[0,1]
	v_lshlrev_b32_e32 v30, 16, v60
	v_and_b32_e32 v31, 0xffff0000, v60
	v_pk_fma_f32 v[32:33], v[22:23], v[32:33], v[34:35]
	v_lshlrev_b32_e32 v6, 16, v53
	v_pk_fma_f32 v[30:31], v[18:19], v[30:31], v[32:33] op_sel_hi:[0,1,1]
	v_cvt_pk_bf16_f32 v2, v30, v31
	v_lshlrev_b32_e32 v30, 16, v57
	v_and_b32_e32 v7, 0xffff0000, v57
	v_and_b32_e32 v31, 0xffff0000, v53
	v_pk_mul_f32 v[6:7], v[22:23], v[6:7] op_sel:[1,0] op_sel_hi:[0,1]
	v_lshlrev_b32_e32 v26, 16, v61
	v_and_b32_e32 v27, 0xffff0000, v61
	v_pk_fma_f32 v[6:7], v[22:23], v[30:31], v[6:7]
	v_lshlrev_b32_e32 v30, 16, v54
	v_and_b32_e32 v31, 0xffff0000, v58
	v_pk_fma_f32 v[6:7], v[18:19], v[26:27], v[6:7] op_sel_hi:[0,1,1]
	v_lshlrev_b32_e32 v26, 16, v58
	v_and_b32_e32 v27, 0xffff0000, v54
	v_pk_mul_f32 v[30:31], v[22:23], v[30:31] op_sel:[1,0] op_sel_hi:[0,1]
	v_cvt_pk_bf16_f32 v3, v6, v7
	v_lshlrev_b32_e32 v6, 16, v62
	v_and_b32_e32 v7, 0xffff0000, v62
	v_pk_fma_f32 v[26:27], v[22:23], v[26:27], v[30:31]
	v_lshlrev_b32_e32 v8, 16, v55
	v_pk_fma_f32 v[6:7], v[18:19], v[6:7], v[26:27] op_sel_hi:[0,1,1]
	v_lshlrev_b32_e32 v26, 16, v59
	v_and_b32_e32 v9, 0xffff0000, v59
	v_and_b32_e32 v27, 0xffff0000, v55
	v_pk_mul_f32 v[8:9], v[22:23], v[8:9] op_sel:[1,0] op_sel_hi:[0,1]
	v_cvt_pk_bf16_f32 v4, v6, v7
	v_lshlrev_b32_e32 v6, 16, v63
	v_and_b32_e32 v7, 0xffff0000, v63
	v_pk_fma_f32 v[8:9], v[22:23], v[26:27], v[8:9]
	s_nop 0
	v_pk_fma_f32 v[6:7], v[18:19], v[6:7], v[8:9] op_sel_hi:[0,1,1]
	v_cvt_pk_bf16_f32 v5, v6, v7
	global_store_dwordx4 v[20:21], v[2:5], off offset:2576
	v_lshlrev_b32_e32 v34, 16, v64
	v_and_b32_e32 v35, 0xffff0000, v68
	v_lshlrev_b32_e32 v32, 16, v68
	v_and_b32_e32 v33, 0xffff0000, v64
	v_pk_mul_f32 v[34:35], v[22:23], v[34:35] op_sel:[1,0] op_sel_hi:[0,1]
	v_lshlrev_b32_e32 v30, 16, v72
	v_and_b32_e32 v31, 0xffff0000, v72
	v_pk_fma_f32 v[32:33], v[22:23], v[32:33], v[34:35]
	v_lshlrev_b32_e32 v6, 16, v65
	v_pk_fma_f32 v[30:31], v[18:19], v[30:31], v[32:33] op_sel_hi:[0,1,1]
	v_cvt_pk_bf16_f32 v2, v30, v31
	v_lshlrev_b32_e32 v30, 16, v69
	v_and_b32_e32 v7, 0xffff0000, v69
	v_and_b32_e32 v31, 0xffff0000, v65
	v_pk_mul_f32 v[6:7], v[22:23], v[6:7] op_sel:[1,0] op_sel_hi:[0,1]
	v_lshlrev_b32_e32 v26, 16, v73
	v_and_b32_e32 v27, 0xffff0000, v73
	v_pk_fma_f32 v[6:7], v[22:23], v[30:31], v[6:7]
	v_lshlrev_b32_e32 v30, 16, v66
	v_and_b32_e32 v31, 0xffff0000, v70
	v_pk_fma_f32 v[6:7], v[18:19], v[26:27], v[6:7] op_sel_hi:[0,1,1]
	v_lshlrev_b32_e32 v26, 16, v70
	v_and_b32_e32 v27, 0xffff0000, v66
	v_pk_mul_f32 v[30:31], v[22:23], v[30:31] op_sel:[1,0] op_sel_hi:[0,1]
	v_cvt_pk_bf16_f32 v3, v6, v7
	v_lshlrev_b32_e32 v6, 16, v74
	v_and_b32_e32 v7, 0xffff0000, v74
	v_pk_fma_f32 v[26:27], v[22:23], v[26:27], v[30:31]
	v_lshlrev_b32_e32 v8, 16, v67
	v_pk_fma_f32 v[6:7], v[18:19], v[6:7], v[26:27] op_sel_hi:[0,1,1]
	v_lshlrev_b32_e32 v26, 16, v71
	v_and_b32_e32 v9, 0xffff0000, v71
	v_and_b32_e32 v27, 0xffff0000, v67
	v_pk_mul_f32 v[8:9], v[22:23], v[8:9] op_sel:[1,0] op_sel_hi:[0,1]
	v_cvt_pk_bf16_f32 v4, v6, v7
	v_lshlrev_b32_e32 v6, 16, v75
	v_and_b32_e32 v7, 0xffff0000, v75
	v_pk_fma_f32 v[8:9], v[22:23], v[26:27], v[8:9]
	s_nop 0
	v_pk_fma_f32 v[6:7], v[18:19], v[6:7], v[8:9] op_sel_hi:[0,1,1]
	v_cvt_pk_bf16_f32 v5, v6, v7
	global_store_dwordx4 v[20:21], v[2:5], off offset:2592
	v_lshlrev_b32_e32 v34, 16, v76
	v_and_b32_e32 v35, 0xffff0000, v80
	v_lshlrev_b32_e32 v32, 16, v80
	v_and_b32_e32 v33, 0xffff0000, v76
	v_pk_mul_f32 v[34:35], v[22:23], v[34:35] op_sel:[1,0] op_sel_hi:[0,1]
	v_lshlrev_b32_e32 v30, 16, v84
	v_and_b32_e32 v31, 0xffff0000, v84
	v_pk_fma_f32 v[32:33], v[22:23], v[32:33], v[34:35]
	v_lshlrev_b32_e32 v6, 16, v77
	v_pk_fma_f32 v[30:31], v[18:19], v[30:31], v[32:33] op_sel_hi:[0,1,1]
	v_cvt_pk_bf16_f32 v2, v30, v31
	v_lshlrev_b32_e32 v30, 16, v81
	v_and_b32_e32 v7, 0xffff0000, v81
	v_and_b32_e32 v31, 0xffff0000, v77
	v_pk_mul_f32 v[6:7], v[22:23], v[6:7] op_sel:[1,0] op_sel_hi:[0,1]
	v_lshlrev_b32_e32 v26, 16, v85
	v_and_b32_e32 v27, 0xffff0000, v85
	v_pk_fma_f32 v[6:7], v[22:23], v[30:31], v[6:7]
	v_lshlrev_b32_e32 v30, 16, v78
	v_and_b32_e32 v31, 0xffff0000, v82
	v_pk_fma_f32 v[6:7], v[18:19], v[26:27], v[6:7] op_sel_hi:[0,1,1]
	v_lshlrev_b32_e32 v26, 16, v82
	v_and_b32_e32 v27, 0xffff0000, v78
	v_pk_mul_f32 v[30:31], v[22:23], v[30:31] op_sel:[1,0] op_sel_hi:[0,1]
	v_cvt_pk_bf16_f32 v3, v6, v7
	v_lshlrev_b32_e32 v6, 16, v86
	v_and_b32_e32 v7, 0xffff0000, v86
	v_pk_fma_f32 v[26:27], v[22:23], v[26:27], v[30:31]
	v_lshlrev_b32_e32 v8, 16, v79
	v_pk_fma_f32 v[6:7], v[18:19], v[6:7], v[26:27] op_sel_hi:[0,1,1]
	v_lshlrev_b32_e32 v26, 16, v83
	v_and_b32_e32 v9, 0xffff0000, v83
	v_and_b32_e32 v27, 0xffff0000, v79
	v_pk_mul_f32 v[8:9], v[22:23], v[8:9] op_sel:[1,0] op_sel_hi:[0,1]
	v_cvt_pk_bf16_f32 v4, v6, v7
	v_lshlrev_b32_e32 v6, 16, v87
	v_and_b32_e32 v7, 0xffff0000, v87
	v_pk_fma_f32 v[8:9], v[22:23], v[26:27], v[8:9]
	s_nop 0
	v_pk_fma_f32 v[6:7], v[18:19], v[6:7], v[8:9] op_sel_hi:[0,1,1]
	v_cvt_pk_bf16_f32 v5, v6, v7
	global_store_dwordx4 v[20:21], v[2:5], off offset:2608
	v_lshlrev_b32_e32 v34, 16, v88
	v_and_b32_e32 v35, 0xffff0000, v92
	v_lshlrev_b32_e32 v32, 16, v92
	v_and_b32_e32 v33, 0xffff0000, v88
	v_pk_mul_f32 v[34:35], v[22:23], v[34:35] op_sel:[1,0] op_sel_hi:[0,1]
	v_lshlrev_b32_e32 v30, 16, v96
	v_and_b32_e32 v31, 0xffff0000, v96
	v_pk_fma_f32 v[32:33], v[22:23], v[32:33], v[34:35]
	v_lshlrev_b32_e32 v6, 16, v89
	v_pk_fma_f32 v[30:31], v[18:19], v[30:31], v[32:33] op_sel_hi:[0,1,1]
	v_cvt_pk_bf16_f32 v2, v30, v31
	v_lshlrev_b32_e32 v30, 16, v93
	v_and_b32_e32 v7, 0xffff0000, v93
	v_and_b32_e32 v31, 0xffff0000, v89
	v_pk_mul_f32 v[6:7], v[22:23], v[6:7] op_sel:[1,0] op_sel_hi:[0,1]
	v_lshlrev_b32_e32 v26, 16, v97
	v_and_b32_e32 v27, 0xffff0000, v97
	v_pk_fma_f32 v[6:7], v[22:23], v[30:31], v[6:7]
	v_lshlrev_b32_e32 v30, 16, v90
	v_and_b32_e32 v31, 0xffff0000, v94
	v_pk_fma_f32 v[6:7], v[18:19], v[26:27], v[6:7] op_sel_hi:[0,1,1]
	v_lshlrev_b32_e32 v26, 16, v94
	v_and_b32_e32 v27, 0xffff0000, v90
	v_pk_mul_f32 v[30:31], v[22:23], v[30:31] op_sel:[1,0] op_sel_hi:[0,1]
	v_cvt_pk_bf16_f32 v3, v6, v7
	v_lshlrev_b32_e32 v6, 16, v98
	v_and_b32_e32 v7, 0xffff0000, v98
	v_pk_fma_f32 v[26:27], v[22:23], v[26:27], v[30:31]
	v_lshlrev_b32_e32 v8, 16, v91
	v_pk_fma_f32 v[6:7], v[18:19], v[6:7], v[26:27] op_sel_hi:[0,1,1]
	v_lshlrev_b32_e32 v26, 16, v95
	v_and_b32_e32 v9, 0xffff0000, v95
	v_and_b32_e32 v27, 0xffff0000, v91
	v_pk_mul_f32 v[8:9], v[22:23], v[8:9] op_sel:[1,0] op_sel_hi:[0,1]
	v_cvt_pk_bf16_f32 v4, v6, v7
	v_lshlrev_b32_e32 v6, 16, v99
	v_and_b32_e32 v7, 0xffff0000, v99
	v_pk_fma_f32 v[8:9], v[22:23], v[26:27], v[8:9]
	s_nop 0
	v_pk_fma_f32 v[6:7], v[18:19], v[6:7], v[8:9] op_sel_hi:[0,1,1]
	v_cvt_pk_bf16_f32 v5, v6, v7
	global_store_dwordx4 v[20:21], v[2:5], off offset:2624
	v_lshlrev_b32_e32 v34, 16, v100
	v_and_b32_e32 v35, 0xffff0000, v104
	v_lshlrev_b32_e32 v32, 16, v104
	v_and_b32_e32 v33, 0xffff0000, v100
	v_pk_mul_f32 v[34:35], v[22:23], v[34:35] op_sel:[1,0] op_sel_hi:[0,1]
	v_lshlrev_b32_e32 v30, 16, v108
	v_and_b32_e32 v31, 0xffff0000, v108
	v_pk_fma_f32 v[32:33], v[22:23], v[32:33], v[34:35]
	v_lshlrev_b32_e32 v6, 16, v101
	v_pk_fma_f32 v[30:31], v[18:19], v[30:31], v[32:33] op_sel_hi:[0,1,1]
	v_cvt_pk_bf16_f32 v2, v30, v31
	v_lshlrev_b32_e32 v30, 16, v105
	v_and_b32_e32 v7, 0xffff0000, v105
	v_and_b32_e32 v31, 0xffff0000, v101
	v_pk_mul_f32 v[6:7], v[22:23], v[6:7] op_sel:[1,0] op_sel_hi:[0,1]
	v_lshlrev_b32_e32 v26, 16, v109
	v_and_b32_e32 v27, 0xffff0000, v109
	v_pk_fma_f32 v[6:7], v[22:23], v[30:31], v[6:7]
	v_lshlrev_b32_e32 v30, 16, v102
	v_and_b32_e32 v31, 0xffff0000, v106
	v_pk_fma_f32 v[6:7], v[18:19], v[26:27], v[6:7] op_sel_hi:[0,1,1]
	v_lshlrev_b32_e32 v26, 16, v106
	v_and_b32_e32 v27, 0xffff0000, v102
	v_pk_mul_f32 v[30:31], v[22:23], v[30:31] op_sel:[1,0] op_sel_hi:[0,1]
	v_cvt_pk_bf16_f32 v3, v6, v7
	v_lshlrev_b32_e32 v6, 16, v110
	v_and_b32_e32 v7, 0xffff0000, v110
	v_pk_fma_f32 v[26:27], v[22:23], v[26:27], v[30:31]
	v_lshlrev_b32_e32 v8, 16, v103
	v_pk_fma_f32 v[6:7], v[18:19], v[6:7], v[26:27] op_sel_hi:[0,1,1]
	v_lshlrev_b32_e32 v26, 16, v107
	v_and_b32_e32 v9, 0xffff0000, v107
	v_and_b32_e32 v27, 0xffff0000, v103
	v_pk_mul_f32 v[8:9], v[22:23], v[8:9] op_sel:[1,0] op_sel_hi:[0,1]
	v_cvt_pk_bf16_f32 v4, v6, v7
	v_lshlrev_b32_e32 v6, 16, v111
	v_and_b32_e32 v7, 0xffff0000, v111
	v_pk_fma_f32 v[8:9], v[22:23], v[26:27], v[8:9]
	s_nop 0
	v_pk_fma_f32 v[6:7], v[18:19], v[6:7], v[8:9] op_sel_hi:[0,1,1]
	v_cvt_pk_bf16_f32 v5, v6, v7
	global_store_dwordx4 v[20:21], v[2:5], off offset:2640
	v_lshlrev_b32_e32 v34, 16, v112
	v_and_b32_e32 v35, 0xffff0000, v116
	v_lshlrev_b32_e32 v32, 16, v116
	v_and_b32_e32 v33, 0xffff0000, v112
	v_pk_mul_f32 v[34:35], v[22:23], v[34:35] op_sel:[1,0] op_sel_hi:[0,1]
	v_lshlrev_b32_e32 v30, 16, v124
	v_and_b32_e32 v31, 0xffff0000, v124
	v_pk_fma_f32 v[32:33], v[22:23], v[32:33], v[34:35]
	v_lshlrev_b32_e32 v6, 16, v113
	v_pk_fma_f32 v[30:31], v[18:19], v[30:31], v[32:33] op_sel_hi:[0,1,1]
	v_cvt_pk_bf16_f32 v2, v30, v31
	v_lshlrev_b32_e32 v30, 16, v117
	v_and_b32_e32 v7, 0xffff0000, v117
	v_and_b32_e32 v31, 0xffff0000, v113
	v_pk_mul_f32 v[6:7], v[22:23], v[6:7] op_sel:[1,0] op_sel_hi:[0,1]
	v_lshlrev_b32_e32 v26, 16, v125
	v_and_b32_e32 v27, 0xffff0000, v125
	v_pk_fma_f32 v[6:7], v[22:23], v[30:31], v[6:7]
	v_lshlrev_b32_e32 v30, 16, v114
	v_and_b32_e32 v31, 0xffff0000, v118
	v_pk_fma_f32 v[6:7], v[18:19], v[26:27], v[6:7] op_sel_hi:[0,1,1]
	v_lshlrev_b32_e32 v26, 16, v118
	v_and_b32_e32 v27, 0xffff0000, v114
	v_pk_mul_f32 v[30:31], v[22:23], v[30:31] op_sel:[1,0] op_sel_hi:[0,1]
	v_cvt_pk_bf16_f32 v3, v6, v7
	v_lshlrev_b32_e32 v6, 16, v126
	v_and_b32_e32 v7, 0xffff0000, v126
	v_pk_fma_f32 v[26:27], v[22:23], v[26:27], v[30:31]
	v_lshlrev_b32_e32 v8, 16, v115
	v_pk_fma_f32 v[6:7], v[18:19], v[6:7], v[26:27] op_sel_hi:[0,1,1]
	v_lshlrev_b32_e32 v26, 16, v119
	v_and_b32_e32 v9, 0xffff0000, v119
	v_and_b32_e32 v27, 0xffff0000, v115
	v_pk_mul_f32 v[8:9], v[22:23], v[8:9] op_sel:[1,0] op_sel_hi:[0,1]
	v_cvt_pk_bf16_f32 v4, v6, v7
	v_lshlrev_b32_e32 v6, 16, v127
	v_and_b32_e32 v7, 0xffff0000, v127
	v_pk_fma_f32 v[8:9], v[22:23], v[26:27], v[8:9]
	s_nop 0
	v_pk_fma_f32 v[6:7], v[18:19], v[6:7], v[8:9] op_sel_hi:[0,1,1]
	v_cvt_pk_bf16_f32 v5, v6, v7
	global_store_dwordx4 v[20:21], v[2:5], off offset:2656
	v_lshlrev_b32_e32 v32, 16, v128
	v_and_b32_e32 v33, 0xffff0000, v132
	v_lshlrev_b32_e32 v30, 16, v132
	v_and_b32_e32 v31, 0xffff0000, v128
	v_pk_mul_f32 v[32:33], v[22:23], v[32:33] op_sel:[1,0] op_sel_hi:[0,1]
	v_lshlrev_b32_e32 v28, 16, v136
	v_and_b32_e32 v29, 0xffff0000, v136
	v_pk_fma_f32 v[30:31], v[22:23], v[30:31], v[32:33]
	v_lshlrev_b32_e32 v6, 16, v129
	v_pk_fma_f32 v[28:29], v[18:19], v[28:29], v[30:31] op_sel_hi:[0,1,1]
	v_cvt_pk_bf16_f32 v2, v28, v29
	v_lshlrev_b32_e32 v28, 16, v133
	v_and_b32_e32 v7, 0xffff0000, v133
	v_and_b32_e32 v29, 0xffff0000, v129
	v_pk_mul_f32 v[6:7], v[22:23], v[6:7] op_sel:[1,0] op_sel_hi:[0,1]
	v_lshlrev_b32_e32 v24, 16, v137
	v_and_b32_e32 v25, 0xffff0000, v137
	v_pk_fma_f32 v[6:7], v[22:23], v[28:29], v[6:7]
	v_lshlrev_b32_e32 v28, 16, v130
	v_and_b32_e32 v29, 0xffff0000, v134
	v_pk_fma_f32 v[6:7], v[18:19], v[24:25], v[6:7] op_sel_hi:[0,1,1]
	v_lshlrev_b32_e32 v24, 16, v134
	v_and_b32_e32 v25, 0xffff0000, v130
	v_pk_mul_f32 v[28:29], v[22:23], v[28:29] op_sel:[1,0] op_sel_hi:[0,1]
	v_cvt_pk_bf16_f32 v3, v6, v7
	v_lshlrev_b32_e32 v6, 16, v138
	v_and_b32_e32 v7, 0xffff0000, v138
	v_pk_fma_f32 v[24:25], v[22:23], v[24:25], v[28:29]
	v_lshlrev_b32_e32 v8, 16, v131
	v_pk_fma_f32 v[6:7], v[18:19], v[6:7], v[24:25] op_sel_hi:[0,1,1]
	v_lshlrev_b32_e32 v24, 16, v135
	v_and_b32_e32 v9, 0xffff0000, v135
	v_and_b32_e32 v25, 0xffff0000, v131
	v_pk_mul_f32 v[8:9], v[22:23], v[8:9] op_sel:[1,0] op_sel_hi:[0,1]
	v_cvt_pk_bf16_f32 v4, v6, v7
	v_lshlrev_b32_e32 v6, 16, v139
	v_and_b32_e32 v7, 0xffff0000, v139
	v_pk_fma_f32 v[8:9], v[22:23], v[24:25], v[8:9]
	s_nop 0
	v_pk_fma_f32 v[6:7], v[18:19], v[6:7], v[8:9] op_sel_hi:[0,1,1]
	v_cvt_pk_bf16_f32 v5, v6, v7
	global_store_dwordx4 v[20:21], v[2:5], off offset:2672
	global_load_dword v4, v[16:17], off offset:4
	s_nop 0
	v_or_b32_e32 v5, 1, v19
	v_lshlrev_b32_e32 v0, 2, v5
	v_lshl_add_u64 v[2:3], v[14:15], 0, v[0:1]
	global_load_dword v6, v[2:3], off
	v_lshl_add_u64 v[2:3], v[12:13], 0, v[0:1]
	global_load_dword v0, v[2:3], off
	s_waitcnt vmcnt(0) lgkmcnt(0)
	v_max3_f32 v7, v4, v6, v0
	v_sub_f32_e32 v2, v4, v7
	v_mul_f32_e32 v2, 0x3fb8aa3b, v2
	v_exp_f32_e32 v3, v2
	v_sub_f32_e32 v2, v6, v7
	v_mul_f32_e32 v2, 0x3fb8aa3b, v2
	v_sub_f32_e32 v0, v0, v7
	v_exp_f32_e32 v2, v2
	v_mul_f32_e32 v0, 0x3fb8aa3b, v0
	v_exp_f32_e32 v0, v0
	v_add_f32_e32 v4, v3, v2
	v_add_f32_e32 v4, v0, v4
	v_div_scale_f32 v6, s[6:7], v4, v4, 1.0
	v_rcp_f32_e32 v7, v6
	s_nop 0
	v_fma_f32 v8, -v6, v7, 1.0
	v_fmac_f32_e32 v7, v8, v7
	v_div_scale_f32 v8, vcc, 1.0, v4, 1.0
	v_mul_f32_e32 v9, v8, v7
	v_fma_f32 v12, -v6, v9, v8
	v_fmac_f32_e32 v9, v12, v7
	v_fma_f32 v6, -v6, v9, v8
	v_div_fmas_f32 v6, v6, v7, v9
	v_div_fixup_f32 v4, v6, v4, 1.0
	v_mul_f32_e32 v14, v0, v4
	v_lshlrev_b32_e32 v0, 7, v5
	v_lshl_add_u64 v[16:17], v[10:11], 0, v[0:1]
	global_load_dwordx4 v[40:43], v[16:17], off offset:2560
	global_load_dwordx4 v[44:47], v[16:17], off offset:3584
	v_add_co_u32_e32 v10, vcc, s53, v16
	v_pk_mul_f32 v[18:19], v[2:3], v[4:5] op_sel_hi:[1,0]
	s_nop 0
	v_addc_co_u32_e32 v11, vcc, 0, v17, vcc
	global_load_dwordx4 v[48:51], v[10:11], off
	global_load_dwordx4 v[52:55], v[16:17], off offset:2576
	s_nop 0
	global_load_dwordx4 v[56:59], v[16:17], off offset:3600
	global_load_dwordx4 v[60:63], v[10:11], off offset:16
	global_load_dwordx4 v[64:67], v[16:17], off offset:2592
	s_nop 0
	global_load_dwordx4 v[68:71], v[16:17], off offset:3616
	global_load_dwordx4 v[72:75], v[10:11], off offset:32
	global_load_dwordx4 v[76:79], v[16:17], off offset:2608
	s_nop 0
	global_load_dwordx4 v[80:83], v[16:17], off offset:3632
	global_load_dwordx4 v[84:87], v[10:11], off offset:48
	global_load_dwordx4 v[88:91], v[16:17], off offset:2624
	s_nop 0
	global_load_dwordx4 v[92:95], v[16:17], off offset:3648
	global_load_dwordx4 v[96:99], v[10:11], off offset:64
	global_load_dwordx4 v[100:103], v[16:17], off offset:2640
	s_nop 0
	global_load_dwordx4 v[104:107], v[16:17], off offset:3664
	global_load_dwordx4 v[108:111], v[10:11], off offset:80
	global_load_dwordx4 v[112:115], v[16:17], off offset:2656
	s_nop 0
	global_load_dwordx4 v[116:119], v[16:17], off offset:3680
	global_load_dwordx4 v[124:127], v[10:11], off offset:96
	global_load_dwordx4 v[128:131], v[16:17], off offset:2672
	s_nop 0
	global_load_dwordx4 v[132:135], v[16:17], off offset:3696
	s_nop 0
	global_load_dwordx4 v[136:139], v[10:11], off offset:112
	s_waitcnt vmcnt(0) lgkmcnt(0)
	v_lshlrev_b32_e32 v4, 16, v40
	v_and_b32_e32 v5, 0xffff0000, v44
	v_lshlrev_b32_e32 v2, 16, v44
	v_and_b32_e32 v3, 0xffff0000, v40
	v_pk_mul_f32 v[4:5], v[18:19], v[4:5] op_sel:[1,0] op_sel_hi:[0,1]
	v_pk_fma_f32 v[2:3], v[18:19], v[2:3], v[4:5]
	v_and_b32_e32 v5, 0xffff0000, v41
	v_lshlrev_b32_e32 v6, 16, v41
	v_and_b32_e32 v7, 0xffff0000, v45
	v_lshlrev_b32_e32 v4, 16, v45
	v_pk_mul_f32 v[6:7], v[18:19], v[6:7] op_sel:[1,0] op_sel_hi:[0,1]
	v_lshlrev_b32_e32 v12, 16, v48
	v_and_b32_e32 v13, 0xffff0000, v48
	v_lshlrev_b32_e32 v24, 16, v49
	v_and_b32_e32 v25, 0xffff0000, v49
	v_pk_fma_f32 v[4:5], v[18:19], v[4:5], v[6:7]
	v_pk_fma_f32 v[2:3], v[14:15], v[12:13], v[2:3] op_sel_hi:[0,1,1]
	v_pk_fma_f32 v[4:5], v[14:15], v[24:25], v[4:5] op_sel_hi:[0,1,1]
	v_lshlrev_b32_e32 v6, 16, v42
	v_and_b32_e32 v7, 0xffff0000, v46
	v_cvt_pk_bf16_f32 v2, v2, v3
	v_cvt_pk_bf16_f32 v3, v4, v5
	v_lshlrev_b32_e32 v4, 16, v46
	v_and_b32_e32 v5, 0xffff0000, v42
	v_pk_mul_f32 v[6:7], v[18:19], v[6:7] op_sel:[1,0] op_sel_hi:[0,1]
	v_pk_fma_f32 v[4:5], v[18:19], v[4:5], v[6:7]
	v_and_b32_e32 v7, 0xffff0000, v43
	v_lshlrev_b32_e32 v8, 16, v43
	v_and_b32_e32 v9, 0xffff0000, v47
	v_lshlrev_b32_e32 v6, 16, v47
	v_pk_mul_f32 v[8:9], v[18:19], v[8:9] op_sel:[1,0] op_sel_hi:[0,1]
	v_lshlrev_b32_e32 v28, 16, v50
	v_and_b32_e32 v29, 0xffff0000, v50
	v_lshlrev_b32_e32 v26, 16, v51
	v_and_b32_e32 v27, 0xffff0000, v51
	v_pk_fma_f32 v[6:7], v[18:19], v[6:7], v[8:9]
	v_pk_fma_f32 v[4:5], v[14:15], v[28:29], v[4:5] op_sel_hi:[0,1,1]
	v_pk_fma_f32 v[6:7], v[14:15], v[26:27], v[6:7] op_sel_hi:[0,1,1]
	v_cvt_pk_bf16_f32 v4, v4, v5
	v_cvt_pk_bf16_f32 v5, v6, v7
	global_store_dwordx4 v[16:17], v[2:5], off offset:2560
	v_lshlrev_b32_e32 v26, 16, v52
	v_and_b32_e32 v27, 0xffff0000, v56
	v_lshlrev_b32_e32 v24, 16, v56
	v_and_b32_e32 v25, 0xffff0000, v52
	v_pk_mul_f32 v[26:27], v[18:19], v[26:27] op_sel:[1,0] op_sel_hi:[0,1]
	v_lshlrev_b32_e32 v12, 16, v60
	v_and_b32_e32 v13, 0xffff0000, v60
	v_pk_fma_f32 v[24:25], v[18:19], v[24:25], v[26:27]
	v_lshlrev_b32_e32 v20, 16, v57
	v_pk_fma_f32 v[12:13], v[14:15], v[12:13], v[24:25] op_sel_hi:[0,1,1]
	v_lshlrev_b32_e32 v6, 16, v53
	v_and_b32_e32 v7, 0xffff0000, v57
	v_cvt_pk_bf16_f32 v2, v12, v13
	v_lshlrev_b32_e32 v12, 16, v61
	v_and_b32_e32 v13, 0xffff0000, v61
	v_and_b32_e32 v21, 0xffff0000, v53
	v_pk_mul_f32 v[6:7], v[18:19], v[6:7] op_sel:[1,0] op_sel_hi:[0,1]
	v_pk_fma_f32 v[6:7], v[18:19], v[20:21], v[6:7]
	v_lshlrev_b32_e32 v20, 16, v54
	v_and_b32_e32 v21, 0xffff0000, v58
	v_pk_fma_f32 v[6:7], v[14:15], v[12:13], v[6:7] op_sel_hi:[0,1,1]
	v_lshlrev_b32_e32 v12, 16, v58
	v_and_b32_e32 v13, 0xffff0000, v54
	v_pk_mul_f32 v[20:21], v[18:19], v[20:21] op_sel:[1,0] op_sel_hi:[0,1]
	v_cvt_pk_bf16_f32 v3, v6, v7
	v_lshlrev_b32_e32 v6, 16, v62
	v_and_b32_e32 v7, 0xffff0000, v62
	v_pk_fma_f32 v[12:13], v[18:19], v[12:13], v[20:21]
	v_lshlrev_b32_e32 v8, 16, v55
	v_pk_fma_f32 v[6:7], v[14:15], v[6:7], v[12:13] op_sel_hi:[0,1,1]
	v_lshlrev_b32_e32 v12, 16, v59
	v_and_b32_e32 v9, 0xffff0000, v59
	v_and_b32_e32 v13, 0xffff0000, v55
	v_pk_mul_f32 v[8:9], v[18:19], v[8:9] op_sel:[1,0] op_sel_hi:[0,1]
	v_cvt_pk_bf16_f32 v4, v6, v7
	v_lshlrev_b32_e32 v6, 16, v63
	v_and_b32_e32 v7, 0xffff0000, v63
	v_pk_fma_f32 v[8:9], v[18:19], v[12:13], v[8:9]
	s_nop 0
	v_pk_fma_f32 v[6:7], v[14:15], v[6:7], v[8:9] op_sel_hi:[0,1,1]
	v_cvt_pk_bf16_f32 v5, v6, v7
	global_store_dwordx4 v[16:17], v[2:5], off offset:2576
	v_lshlrev_b32_e32 v26, 16, v64
	v_and_b32_e32 v27, 0xffff0000, v68
	v_lshlrev_b32_e32 v24, 16, v68
	v_and_b32_e32 v25, 0xffff0000, v64
	v_pk_mul_f32 v[26:27], v[18:19], v[26:27] op_sel:[1,0] op_sel_hi:[0,1]
	v_lshlrev_b32_e32 v12, 16, v72
	v_and_b32_e32 v13, 0xffff0000, v72
	v_pk_fma_f32 v[24:25], v[18:19], v[24:25], v[26:27]
	v_lshlrev_b32_e32 v20, 16, v69
	v_pk_fma_f32 v[12:13], v[14:15], v[12:13], v[24:25] op_sel_hi:[0,1,1]
	v_lshlrev_b32_e32 v6, 16, v65
	v_and_b32_e32 v7, 0xffff0000, v69
	v_cvt_pk_bf16_f32 v2, v12, v13
	v_lshlrev_b32_e32 v12, 16, v73
	v_and_b32_e32 v13, 0xffff0000, v73
	v_and_b32_e32 v21, 0xffff0000, v65
	v_pk_mul_f32 v[6:7], v[18:19], v[6:7] op_sel:[1,0] op_sel_hi:[0,1]
	v_pk_fma_f32 v[6:7], v[18:19], v[20:21], v[6:7]
	v_lshlrev_b32_e32 v20, 16, v66
	v_and_b32_e32 v21, 0xffff0000, v70
	v_pk_fma_f32 v[6:7], v[14:15], v[12:13], v[6:7] op_sel_hi:[0,1,1]
	v_lshlrev_b32_e32 v12, 16, v70
	v_and_b32_e32 v13, 0xffff0000, v66
	v_pk_mul_f32 v[20:21], v[18:19], v[20:21] op_sel:[1,0] op_sel_hi:[0,1]
	v_cvt_pk_bf16_f32 v3, v6, v7
	v_lshlrev_b32_e32 v6, 16, v74
	v_and_b32_e32 v7, 0xffff0000, v74
	v_pk_fma_f32 v[12:13], v[18:19], v[12:13], v[20:21]
	v_lshlrev_b32_e32 v8, 16, v67
	v_pk_fma_f32 v[6:7], v[14:15], v[6:7], v[12:13] op_sel_hi:[0,1,1]
	v_lshlrev_b32_e32 v12, 16, v71
	v_and_b32_e32 v9, 0xffff0000, v71
	v_and_b32_e32 v13, 0xffff0000, v67
	v_pk_mul_f32 v[8:9], v[18:19], v[8:9] op_sel:[1,0] op_sel_hi:[0,1]
	v_cvt_pk_bf16_f32 v4, v6, v7
	v_lshlrev_b32_e32 v6, 16, v75
	v_and_b32_e32 v7, 0xffff0000, v75
	v_pk_fma_f32 v[8:9], v[18:19], v[12:13], v[8:9]
	s_nop 0
	v_pk_fma_f32 v[6:7], v[14:15], v[6:7], v[8:9] op_sel_hi:[0,1,1]
	v_cvt_pk_bf16_f32 v5, v6, v7
	global_store_dwordx4 v[16:17], v[2:5], off offset:2592
	v_lshlrev_b32_e32 v26, 16, v76
	v_and_b32_e32 v27, 0xffff0000, v80
	v_lshlrev_b32_e32 v24, 16, v80
	v_and_b32_e32 v25, 0xffff0000, v76
	v_pk_mul_f32 v[26:27], v[18:19], v[26:27] op_sel:[1,0] op_sel_hi:[0,1]
	v_lshlrev_b32_e32 v12, 16, v84
	v_and_b32_e32 v13, 0xffff0000, v84
	v_pk_fma_f32 v[24:25], v[18:19], v[24:25], v[26:27]
	v_lshlrev_b32_e32 v20, 16, v81
	v_pk_fma_f32 v[12:13], v[14:15], v[12:13], v[24:25] op_sel_hi:[0,1,1]
	v_lshlrev_b32_e32 v6, 16, v77
	v_and_b32_e32 v7, 0xffff0000, v81
	v_cvt_pk_bf16_f32 v2, v12, v13
	v_lshlrev_b32_e32 v12, 16, v85
	v_and_b32_e32 v13, 0xffff0000, v85
	v_and_b32_e32 v21, 0xffff0000, v77
	v_pk_mul_f32 v[6:7], v[18:19], v[6:7] op_sel:[1,0] op_sel_hi:[0,1]
	v_pk_fma_f32 v[6:7], v[18:19], v[20:21], v[6:7]
	v_lshlrev_b32_e32 v20, 16, v78
	v_and_b32_e32 v21, 0xffff0000, v82
	v_pk_fma_f32 v[6:7], v[14:15], v[12:13], v[6:7] op_sel_hi:[0,1,1]
	v_lshlrev_b32_e32 v12, 16, v82
	v_and_b32_e32 v13, 0xffff0000, v78
	v_pk_mul_f32 v[20:21], v[18:19], v[20:21] op_sel:[1,0] op_sel_hi:[0,1]
	v_cvt_pk_bf16_f32 v3, v6, v7
	v_lshlrev_b32_e32 v6, 16, v86
	v_and_b32_e32 v7, 0xffff0000, v86
	v_pk_fma_f32 v[12:13], v[18:19], v[12:13], v[20:21]
	v_lshlrev_b32_e32 v8, 16, v79
	v_pk_fma_f32 v[6:7], v[14:15], v[6:7], v[12:13] op_sel_hi:[0,1,1]
	v_lshlrev_b32_e32 v12, 16, v83
	v_and_b32_e32 v9, 0xffff0000, v83
	v_and_b32_e32 v13, 0xffff0000, v79
	v_pk_mul_f32 v[8:9], v[18:19], v[8:9] op_sel:[1,0] op_sel_hi:[0,1]
	v_cvt_pk_bf16_f32 v4, v6, v7
	v_lshlrev_b32_e32 v6, 16, v87
	v_and_b32_e32 v7, 0xffff0000, v87
	v_pk_fma_f32 v[8:9], v[18:19], v[12:13], v[8:9]
	s_nop 0
	v_pk_fma_f32 v[6:7], v[14:15], v[6:7], v[8:9] op_sel_hi:[0,1,1]
	v_cvt_pk_bf16_f32 v5, v6, v7
	global_store_dwordx4 v[16:17], v[2:5], off offset:2608
	v_lshlrev_b32_e32 v26, 16, v88
	v_and_b32_e32 v27, 0xffff0000, v92
	v_lshlrev_b32_e32 v24, 16, v92
	v_and_b32_e32 v25, 0xffff0000, v88
	v_pk_mul_f32 v[26:27], v[18:19], v[26:27] op_sel:[1,0] op_sel_hi:[0,1]
	v_lshlrev_b32_e32 v12, 16, v96
	v_and_b32_e32 v13, 0xffff0000, v96
	v_pk_fma_f32 v[24:25], v[18:19], v[24:25], v[26:27]
	v_lshlrev_b32_e32 v20, 16, v93
	v_pk_fma_f32 v[12:13], v[14:15], v[12:13], v[24:25] op_sel_hi:[0,1,1]
	v_lshlrev_b32_e32 v6, 16, v89
	v_and_b32_e32 v7, 0xffff0000, v93
	v_cvt_pk_bf16_f32 v2, v12, v13
	v_lshlrev_b32_e32 v12, 16, v97
	v_and_b32_e32 v13, 0xffff0000, v97
	v_and_b32_e32 v21, 0xffff0000, v89
	v_pk_mul_f32 v[6:7], v[18:19], v[6:7] op_sel:[1,0] op_sel_hi:[0,1]
	v_pk_fma_f32 v[6:7], v[18:19], v[20:21], v[6:7]
	v_lshlrev_b32_e32 v20, 16, v90
	v_and_b32_e32 v21, 0xffff0000, v94
	v_pk_fma_f32 v[6:7], v[14:15], v[12:13], v[6:7] op_sel_hi:[0,1,1]
	v_lshlrev_b32_e32 v12, 16, v94
	v_and_b32_e32 v13, 0xffff0000, v90
	v_pk_mul_f32 v[20:21], v[18:19], v[20:21] op_sel:[1,0] op_sel_hi:[0,1]
	v_cvt_pk_bf16_f32 v3, v6, v7
	v_lshlrev_b32_e32 v6, 16, v98
	v_and_b32_e32 v7, 0xffff0000, v98
	v_pk_fma_f32 v[12:13], v[18:19], v[12:13], v[20:21]
	v_lshlrev_b32_e32 v8, 16, v91
	v_pk_fma_f32 v[6:7], v[14:15], v[6:7], v[12:13] op_sel_hi:[0,1,1]
	v_lshlrev_b32_e32 v12, 16, v95
	v_and_b32_e32 v9, 0xffff0000, v95
	v_and_b32_e32 v13, 0xffff0000, v91
	v_pk_mul_f32 v[8:9], v[18:19], v[8:9] op_sel:[1,0] op_sel_hi:[0,1]
	v_cvt_pk_bf16_f32 v4, v6, v7
	v_lshlrev_b32_e32 v6, 16, v99
	v_and_b32_e32 v7, 0xffff0000, v99
	v_pk_fma_f32 v[8:9], v[18:19], v[12:13], v[8:9]
	s_nop 0
	v_pk_fma_f32 v[6:7], v[14:15], v[6:7], v[8:9] op_sel_hi:[0,1,1]
	v_cvt_pk_bf16_f32 v5, v6, v7
	global_store_dwordx4 v[16:17], v[2:5], off offset:2624
	v_lshlrev_b32_e32 v26, 16, v100
	v_and_b32_e32 v27, 0xffff0000, v104
	v_lshlrev_b32_e32 v24, 16, v104
	v_and_b32_e32 v25, 0xffff0000, v100
	v_pk_mul_f32 v[26:27], v[18:19], v[26:27] op_sel:[1,0] op_sel_hi:[0,1]
	v_lshlrev_b32_e32 v12, 16, v108
	v_and_b32_e32 v13, 0xffff0000, v108
	v_pk_fma_f32 v[24:25], v[18:19], v[24:25], v[26:27]
	v_lshlrev_b32_e32 v20, 16, v105
	v_pk_fma_f32 v[12:13], v[14:15], v[12:13], v[24:25] op_sel_hi:[0,1,1]
	v_lshlrev_b32_e32 v6, 16, v101
	v_and_b32_e32 v7, 0xffff0000, v105
	v_cvt_pk_bf16_f32 v2, v12, v13
	v_lshlrev_b32_e32 v12, 16, v109
	v_and_b32_e32 v13, 0xffff0000, v109
	v_and_b32_e32 v21, 0xffff0000, v101
	v_pk_mul_f32 v[6:7], v[18:19], v[6:7] op_sel:[1,0] op_sel_hi:[0,1]
	v_pk_fma_f32 v[6:7], v[18:19], v[20:21], v[6:7]
	v_lshlrev_b32_e32 v20, 16, v102
	v_and_b32_e32 v21, 0xffff0000, v106
	v_pk_fma_f32 v[6:7], v[14:15], v[12:13], v[6:7] op_sel_hi:[0,1,1]
	v_lshlrev_b32_e32 v12, 16, v106
	v_and_b32_e32 v13, 0xffff0000, v102
	v_pk_mul_f32 v[20:21], v[18:19], v[20:21] op_sel:[1,0] op_sel_hi:[0,1]
	v_cvt_pk_bf16_f32 v3, v6, v7
	v_lshlrev_b32_e32 v6, 16, v110
	v_and_b32_e32 v7, 0xffff0000, v110
	v_pk_fma_f32 v[12:13], v[18:19], v[12:13], v[20:21]
	v_lshlrev_b32_e32 v8, 16, v103
	v_pk_fma_f32 v[6:7], v[14:15], v[6:7], v[12:13] op_sel_hi:[0,1,1]
	v_lshlrev_b32_e32 v12, 16, v107
	v_and_b32_e32 v9, 0xffff0000, v107
	v_and_b32_e32 v13, 0xffff0000, v103
	v_pk_mul_f32 v[8:9], v[18:19], v[8:9] op_sel:[1,0] op_sel_hi:[0,1]
	v_cvt_pk_bf16_f32 v4, v6, v7
	v_lshlrev_b32_e32 v6, 16, v111
	v_and_b32_e32 v7, 0xffff0000, v111
	v_pk_fma_f32 v[8:9], v[18:19], v[12:13], v[8:9]
	s_nop 0
	v_pk_fma_f32 v[6:7], v[14:15], v[6:7], v[8:9] op_sel_hi:[0,1,1]
	v_cvt_pk_bf16_f32 v5, v6, v7
	global_store_dwordx4 v[16:17], v[2:5], off offset:2640
	v_lshlrev_b32_e32 v26, 16, v112
	v_and_b32_e32 v27, 0xffff0000, v116
	v_lshlrev_b32_e32 v24, 16, v116
	v_and_b32_e32 v25, 0xffff0000, v112
	v_pk_mul_f32 v[26:27], v[18:19], v[26:27] op_sel:[1,0] op_sel_hi:[0,1]
	v_lshlrev_b32_e32 v12, 16, v124
	v_and_b32_e32 v13, 0xffff0000, v124
	v_pk_fma_f32 v[24:25], v[18:19], v[24:25], v[26:27]
	v_lshlrev_b32_e32 v20, 16, v117
	v_pk_fma_f32 v[12:13], v[14:15], v[12:13], v[24:25] op_sel_hi:[0,1,1]
	v_lshlrev_b32_e32 v6, 16, v113
	v_and_b32_e32 v7, 0xffff0000, v117
	v_cvt_pk_bf16_f32 v2, v12, v13
	v_lshlrev_b32_e32 v12, 16, v125
	v_and_b32_e32 v13, 0xffff0000, v125
	v_and_b32_e32 v21, 0xffff0000, v113
	v_pk_mul_f32 v[6:7], v[18:19], v[6:7] op_sel:[1,0] op_sel_hi:[0,1]
	v_pk_fma_f32 v[6:7], v[18:19], v[20:21], v[6:7]
	v_lshlrev_b32_e32 v20, 16, v114
	v_and_b32_e32 v21, 0xffff0000, v118
	v_pk_fma_f32 v[6:7], v[14:15], v[12:13], v[6:7] op_sel_hi:[0,1,1]
	v_lshlrev_b32_e32 v12, 16, v118
	v_and_b32_e32 v13, 0xffff0000, v114
	v_pk_mul_f32 v[20:21], v[18:19], v[20:21] op_sel:[1,0] op_sel_hi:[0,1]
	v_cvt_pk_bf16_f32 v3, v6, v7
	v_lshlrev_b32_e32 v6, 16, v126
	v_and_b32_e32 v7, 0xffff0000, v126
	v_pk_fma_f32 v[12:13], v[18:19], v[12:13], v[20:21]
	v_lshlrev_b32_e32 v8, 16, v115
	v_pk_fma_f32 v[6:7], v[14:15], v[6:7], v[12:13] op_sel_hi:[0,1,1]
	v_lshlrev_b32_e32 v12, 16, v119
	v_and_b32_e32 v9, 0xffff0000, v119
	v_and_b32_e32 v13, 0xffff0000, v115
	v_pk_mul_f32 v[8:9], v[18:19], v[8:9] op_sel:[1,0] op_sel_hi:[0,1]
	v_cvt_pk_bf16_f32 v4, v6, v7
	v_lshlrev_b32_e32 v6, 16, v127
	v_and_b32_e32 v7, 0xffff0000, v127
	v_pk_fma_f32 v[8:9], v[18:19], v[12:13], v[8:9]
	s_nop 0
	v_pk_fma_f32 v[6:7], v[14:15], v[6:7], v[8:9] op_sel_hi:[0,1,1]
	v_cvt_pk_bf16_f32 v5, v6, v7
	global_store_dwordx4 v[16:17], v[2:5], off offset:2656
	v_lshlrev_b32_e32 v24, 16, v128
	v_and_b32_e32 v25, 0xffff0000, v132
	v_lshlrev_b32_e32 v22, 16, v132
	v_and_b32_e32 v23, 0xffff0000, v128
	v_pk_mul_f32 v[24:25], v[18:19], v[24:25] op_sel:[1,0] op_sel_hi:[0,1]
	v_lshlrev_b32_e32 v20, 16, v136
	v_and_b32_e32 v21, 0xffff0000, v136
	v_pk_fma_f32 v[22:23], v[18:19], v[22:23], v[24:25]
	v_lshlrev_b32_e32 v6, 16, v129
	v_pk_fma_f32 v[20:21], v[14:15], v[20:21], v[22:23] op_sel_hi:[0,1,1]
	v_cvt_pk_bf16_f32 v2, v20, v21
	v_lshlrev_b32_e32 v20, 16, v133
	v_and_b32_e32 v7, 0xffff0000, v133
	v_and_b32_e32 v21, 0xffff0000, v129
	v_pk_mul_f32 v[6:7], v[18:19], v[6:7] op_sel:[1,0] op_sel_hi:[0,1]
	v_lshlrev_b32_e32 v10, 16, v137
	v_and_b32_e32 v11, 0xffff0000, v137
	v_pk_fma_f32 v[6:7], v[18:19], v[20:21], v[6:7]
	v_lshlrev_b32_e32 v20, 16, v130
	v_and_b32_e32 v21, 0xffff0000, v134
	v_pk_fma_f32 v[6:7], v[14:15], v[10:11], v[6:7] op_sel_hi:[0,1,1]
	v_lshlrev_b32_e32 v10, 16, v134
	v_and_b32_e32 v11, 0xffff0000, v130
	v_pk_mul_f32 v[20:21], v[18:19], v[20:21] op_sel:[1,0] op_sel_hi:[0,1]
	v_cvt_pk_bf16_f32 v3, v6, v7
	v_lshlrev_b32_e32 v6, 16, v138
	v_and_b32_e32 v7, 0xffff0000, v138
	v_pk_fma_f32 v[10:11], v[18:19], v[10:11], v[20:21]
	v_lshlrev_b32_e32 v8, 16, v131
	v_pk_fma_f32 v[6:7], v[14:15], v[6:7], v[10:11] op_sel_hi:[0,1,1]
	v_lshlrev_b32_e32 v10, 16, v135
	v_and_b32_e32 v9, 0xffff0000, v135
	v_and_b32_e32 v11, 0xffff0000, v131
	v_pk_mul_f32 v[8:9], v[18:19], v[8:9] op_sel:[1,0] op_sel_hi:[0,1]
	v_cvt_pk_bf16_f32 v4, v6, v7
	v_lshlrev_b32_e32 v6, 16, v139
	v_and_b32_e32 v7, 0xffff0000, v139
	v_pk_fma_f32 v[8:9], v[18:19], v[10:11], v[8:9]
	s_nop 0
	v_pk_fma_f32 v[6:7], v[14:15], v[6:7], v[8:9] op_sel_hi:[0,1,1]
	v_cvt_pk_bf16_f32 v5, v6, v7
	global_store_dwordx4 v[16:17], v[2:5], off offset:2672

.LBB0_1933:
	v_readlane_b32 s0, v236, 63
	s_cmp_lg_u32 s0, -1
	s_cselect_b32 s0, s0, 0
	s_cselect_b32 s1, s11, 0
	v_mov_b32_e32 v2, s0
	v_mov_b32_e32 v3, s1
	s_waitcnt lgkmcnt(0)
	s_barrier
	flat_load_dword v0, v[2:3] sc0 sc1
	s_waitcnt vmcnt(0)
	v_readlane_b32 s0, v236, 61
	s_waitcnt lgkmcnt(0)
	s_nop 0
	v_add_u32_e32 v2, s0, v0
	s_movk_i32 s0, 0x1ba4
	v_cmp_gt_i32_e32 vcc, s0, v2
	s_mov_b64 s[0:1], -1
	s_and_saveexec_b64 s[46:47], vcc
	s_cbranch_execz .LBB0_1928
	v_cmp_lt_i32_e32 vcc, 35, v2
	s_and_saveexec_b64 s[0:1], vcc
	s_xor_b64 s[48:49], exec, s[0:1]
	s_cbranch_execz .LBB0_1978
	s_movk_i32 s0, 0xa23
	v_cmp_lt_u32_e32 vcc, s0, v2
	s_and_saveexec_b64 s[0:1], vcc
	s_xor_b64 s[50:51], exec, s[0:1]
	s_cbranch_execz .LBB0_1969
	s_movk_i32 s0, 0xf23
	v_cmp_lt_u32_e32 vcc, s0, v2
	s_and_saveexec_b64 s[0:1], vcc
	s_xor_b64 s[0:1], exec, s[0:1]
	s_cbranch_execz .LBB0_1942
	s_movk_i32 s2, 0x1923
	v_cmp_lt_u32_e32 vcc, s2, v2
	s_and_saveexec_b64 s[2:3], vcc
	s_xor_b64 s[2:3], exec, s[2:3]
	s_cbranch_execz .LBB0_1939
	v_mbcnt_lo_u32_b32 v0, -1, 0
	v_mbcnt_hi_u32_b32 v0, -1, v0
	v_mov_b64_e32 v[4:5], s[16:17]
	v_or_b32_e32 v6, s10, v0
	v_lshl_add_u32 v0, v2, 7, v159
	v_ashrrev_i32_e32 v2, 1, v6
	v_ashrrev_i32_e32 v3, 31, v2
	v_lshl_add_u64 v[2:3], v[2:3], 0, v[0:1]
	v_mad_u64_u32 v[10:11], s[4:5], v2, s33, v[4:5]
	v_lshlrev_b32_e32 v0, 1, v6
	v_mad_i32_i24 v11, v3, s33, v11
	v_and_b32_e32 v19, 2, v0
	v_lshl_add_u64 v[2:3], v[2:3], 4, s[62:63]
	s_mov_b64 s[4:5], 0x140000
	v_lshl_add_u64 v[14:15], v[2:3], 0, s[4:5]
	s_mov_b64 s[4:5], 0x280000
	v_lshlrev_b32_e32 v0, 2, v19
	v_lshl_add_u64 v[12:13], v[2:3], 0, s[4:5]
	v_lshl_add_u64 v[16:17], v[2:3], 0, v[0:1]
	v_lshl_add_u64 v[2:3], v[14:15], 0, v[0:1]
	global_load_dword v4, v[16:17], off
	global_load_dword v5, v[2:3], off
	v_lshl_add_u64 v[2:3], v[12:13], 0, v[0:1]
	global_load_dword v0, v[2:3], off
	s_movk_i32 s8, 0x1000
	s_waitcnt vmcnt(0) lgkmcnt(0)
	v_max3_f32 v2, v4, v5, v0
	v_sub_f32_e32 v3, v4, v2
	v_mul_f32_e32 v3, 0x3fb8aa3b, v3
	v_exp_f32_e32 v23, v3
	v_sub_f32_e32 v3, v5, v2
	v_mul_f32_e32 v3, 0x3fb8aa3b, v3
	v_sub_f32_e32 v0, v0, v2
	v_exp_f32_e32 v22, v3
	v_mul_f32_e32 v0, 0x3fb8aa3b, v0
	v_exp_f32_e32 v0, v0
	v_add_f32_e32 v2, v23, v22
	v_add_f32_e32 v2, v0, v2
	v_div_scale_f32 v3, s[4:5], v2, v2, 1.0
	v_rcp_f32_e32 v4, v3
	s_nop 0
	v_fma_f32 v5, -v3, v4, 1.0
	v_fmac_f32_e32 v4, v5, v4
	v_div_scale_f32 v5, vcc, 1.0, v2, 1.0
	v_mul_f32_e32 v6, v5, v4
	v_fma_f32 v7, -v3, v6, v5
	v_fmac_f32_e32 v6, v7, v4
	v_fma_f32 v3, -v3, v6, v5
	v_div_fmas_f32 v3, v3, v4, v6
	v_div_fixup_f32 v30, v3, v2, 1.0
	v_mul_f32_e32 v18, v0, v30
	v_lshlrev_b32_e32 v0, 7, v19
	v_lshl_add_u64 v[20:21], v[10:11], 0, v[0:1]
	global_load_dwordx4 v[40:43], v[20:21], off offset:2560
	global_load_dwordx4 v[44:47], v[20:21], off offset:3584
	v_add_co_u32_e32 v24, vcc, s8, v20
	v_pk_mul_f32 v[22:23], v[22:23], v[30:31] op_sel_hi:[1,0]
	s_nop 0
	v_addc_co_u32_e32 v25, vcc, 0, v21, vcc
	global_load_dwordx4 v[48:51], v[24:25], off
	global_load_dwordx4 v[52:55], v[20:21], off offset:2576
	s_nop 0
	global_load_dwordx4 v[56:59], v[20:21], off offset:3600
	global_load_dwordx4 v[60:63], v[24:25], off offset:16
	global_load_dwordx4 v[64:67], v[20:21], off offset:2592
	s_nop 0
	global_load_dwordx4 v[68:71], v[20:21], off offset:3616
	global_load_dwordx4 v[72:75], v[24:25], off offset:32
	global_load_dwordx4 v[76:79], v[20:21], off offset:2608
	s_nop 0
	global_load_dwordx4 v[80:83], v[20:21], off offset:3632
	global_load_dwordx4 v[84:87], v[24:25], off offset:48
	global_load_dwordx4 v[88:91], v[20:21], off offset:2624
	s_nop 0
	global_load_dwordx4 v[92:95], v[20:21], off offset:3648
	global_load_dwordx4 v[96:99], v[24:25], off offset:64
	global_load_dwordx4 v[100:103], v[20:21], off offset:2640
	s_nop 0
	global_load_dwordx4 v[104:107], v[20:21], off offset:3664
	global_load_dwordx4 v[108:111], v[24:25], off offset:80
	global_load_dwordx4 v[112:115], v[20:21], off offset:2656
	s_nop 0
	global_load_dwordx4 v[116:119], v[20:21], off offset:3680
	global_load_dwordx4 v[124:127], v[24:25], off offset:96
	global_load_dwordx4 v[128:131], v[20:21], off offset:2672
	s_nop 0
	global_load_dwordx4 v[132:135], v[20:21], off offset:3696
	s_nop 0
	global_load_dwordx4 v[136:139], v[24:25], off offset:112
	s_waitcnt vmcnt(0) lgkmcnt(0)
	v_lshlrev_b32_e32 v36, 16, v40
	v_and_b32_e32 v37, 0xffff0000, v44
	v_lshlrev_b32_e32 v30, 16, v44
	v_and_b32_e32 v31, 0xffff0000, v40
	v_pk_mul_f32 v[36:37], v[22:23], v[36:37] op_sel:[1,0] op_sel_hi:[0,1]
	v_pk_fma_f32 v[30:31], v[22:23], v[30:31], v[36:37]
	v_lshlrev_b32_e32 v6, 16, v41
	v_lshlrev_b32_e32 v32, 16, v48
	v_and_b32_e32 v33, 0xffff0000, v48
	v_pk_fma_f32 v[30:31], v[18:19], v[32:33], v[30:31] op_sel_hi:[0,1,1]
	v_cvt_pk_bf16_f32 v2, v30, v31
	v_lshlrev_b32_e32 v30, 16, v45
	v_and_b32_e32 v7, 0xffff0000, v45
	v_and_b32_e32 v31, 0xffff0000, v41
	v_pk_mul_f32 v[6:7], v[22:23], v[6:7] op_sel:[1,0] op_sel_hi:[0,1]
	v_lshlrev_b32_e32 v26, 16, v49
	v_and_b32_e32 v27, 0xffff0000, v49
	v_pk_fma_f32 v[6:7], v[22:23], v[30:31], v[6:7]
	v_lshlrev_b32_e32 v34, 16, v50
	v_pk_fma_f32 v[6:7], v[18:19], v[26:27], v[6:7] op_sel_hi:[0,1,1]
	v_lshlrev_b32_e32 v26, 16, v42
	v_and_b32_e32 v27, 0xffff0000, v46
	v_cvt_pk_bf16_f32 v3, v6, v7
	v_lshlrev_b32_e32 v6, 16, v46
	v_and_b32_e32 v7, 0xffff0000, v42
	v_pk_mul_f32 v[26:27], v[22:23], v[26:27] op_sel:[1,0] op_sel_hi:[0,1]
	v_and_b32_e32 v35, 0xffff0000, v50
	v_pk_fma_f32 v[6:7], v[22:23], v[6:7], v[26:27]
	v_lshlrev_b32_e32 v8, 16, v43
	v_pk_fma_f32 v[6:7], v[18:19], v[34:35], v[6:7] op_sel_hi:[0,1,1]
	v_cvt_pk_bf16_f32 v4, v6, v7
	v_lshlrev_b32_e32 v6, 16, v47
	v_and_b32_e32 v9, 0xffff0000, v47
	v_and_b32_e32 v7, 0xffff0000, v43
	v_pk_mul_f32 v[8:9], v[22:23], v[8:9] op_sel:[1,0] op_sel_hi:[0,1]
	v_lshlrev_b32_e32 v28, 16, v51
	v_and_b32_e32 v29, 0xffff0000, v51
	v_pk_fma_f32 v[6:7], v[22:23], v[6:7], v[8:9]
	s_nop 0
	v_pk_fma_f32 v[6:7], v[18:19], v[28:29], v[6:7] op_sel_hi:[0,1,1]
	v_cvt_pk_bf16_f32 v5, v6, v7
	global_store_dwordx4 v[20:21], v[2:5], off offset:2560
	v_lshlrev_b32_e32 v34, 16, v52
	v_and_b32_e32 v35, 0xffff0000, v56
	v_lshlrev_b32_e32 v32, 16, v56
	v_and_b32_e32 v33, 0xffff0000, v52
	v_pk_mul_f32 v[34:35], v[22:23], v[34:35] op_sel:[1,0] op_sel_hi:[0,1]
	v_lshlrev_b32_e32 v30, 16, v60
	v_and_b32_e32 v31, 0xffff0000, v60
	v_pk_fma_f32 v[32:33], v[22:23], v[32:33], v[34:35]
	v_lshlrev_b32_e32 v6, 16, v53
	v_pk_fma_f32 v[30:31], v[18:19], v[30:31], v[32:33] op_sel_hi:[0,1,1]
	v_cvt_pk_bf16_f32 v2, v30, v31
	v_lshlrev_b32_e32 v30, 16, v57
	v_and_b32_e32 v7, 0xffff0000, v57
	v_and_b32_e32 v31, 0xffff0000, v53
	v_pk_mul_f32 v[6:7], v[22:23], v[6:7] op_sel:[1,0] op_sel_hi:[0,1]
	v_lshlrev_b32_e32 v26, 16, v61
	v_and_b32_e32 v27, 0xffff0000, v61
	v_pk_fma_f32 v[6:7], v[22:23], v[30:31], v[6:7]
	v_lshlrev_b32_e32 v30, 16, v54
	v_and_b32_e32 v31, 0xffff0000, v58
	v_pk_fma_f32 v[6:7], v[18:19], v[26:27], v[6:7] op_sel_hi:[0,1,1]
	v_lshlrev_b32_e32 v26, 16, v58
	v_and_b32_e32 v27, 0xffff0000, v54
	v_pk_mul_f32 v[30:31], v[22:23], v[30:31] op_sel:[1,0] op_sel_hi:[0,1]
	v_cvt_pk_bf16_f32 v3, v6, v7
	v_lshlrev_b32_e32 v6, 16, v62
	v_and_b32_e32 v7, 0xffff0000, v62
	v_pk_fma_f32 v[26:27], v[22:23], v[26:27], v[30:31]
	v_lshlrev_b32_e32 v8, 16, v55
	v_pk_fma_f32 v[6:7], v[18:19], v[6:7], v[26:27] op_sel_hi:[0,1,1]
	v_lshlrev_b32_e32 v26, 16, v59
	v_and_b32_e32 v9, 0xffff0000, v59
	v_and_b32_e32 v27, 0xffff0000, v55
	v_pk_mul_f32 v[8:9], v[22:23], v[8:9] op_sel:[1,0] op_sel_hi:[0,1]
	v_cvt_pk_bf16_f32 v4, v6, v7
	v_lshlrev_b32_e32 v6, 16, v63
	v_and_b32_e32 v7, 0xffff0000, v63
	v_pk_fma_f32 v[8:9], v[22:23], v[26:27], v[8:9]
	s_nop 0
	v_pk_fma_f32 v[6:7], v[18:19], v[6:7], v[8:9] op_sel_hi:[0,1,1]
	v_cvt_pk_bf16_f32 v5, v6, v7
	global_store_dwordx4 v[20:21], v[2:5], off offset:2576
	v_lshlrev_b32_e32 v34, 16, v64
	v_and_b32_e32 v35, 0xffff0000, v68
	v_lshlrev_b32_e32 v32, 16, v68
	v_and_b32_e32 v33, 0xffff0000, v64
	v_pk_mul_f32 v[34:35], v[22:23], v[34:35] op_sel:[1,0] op_sel_hi:[0,1]
	v_lshlrev_b32_e32 v30, 16, v72
	v_and_b32_e32 v31, 0xffff0000, v72
	v_pk_fma_f32 v[32:33], v[22:23], v[32:33], v[34:35]
	v_lshlrev_b32_e32 v6, 16, v65
	v_pk_fma_f32 v[30:31], v[18:19], v[30:31], v[32:33] op_sel_hi:[0,1,1]
	v_cvt_pk_bf16_f32 v2, v30, v31
	v_lshlrev_b32_e32 v30, 16, v69
	v_and_b32_e32 v7, 0xffff0000, v69
	v_and_b32_e32 v31, 0xffff0000, v65
	v_pk_mul_f32 v[6:7], v[22:23], v[6:7] op_sel:[1,0] op_sel_hi:[0,1]
	v_lshlrev_b32_e32 v26, 16, v73
	v_and_b32_e32 v27, 0xffff0000, v73
	v_pk_fma_f32 v[6:7], v[22:23], v[30:31], v[6:7]
	v_lshlrev_b32_e32 v30, 16, v66
	v_and_b32_e32 v31, 0xffff0000, v70
	v_pk_fma_f32 v[6:7], v[18:19], v[26:27], v[6:7] op_sel_hi:[0,1,1]
	v_lshlrev_b32_e32 v26, 16, v70
	v_and_b32_e32 v27, 0xffff0000, v66
	v_pk_mul_f32 v[30:31], v[22:23], v[30:31] op_sel:[1,0] op_sel_hi:[0,1]
	v_cvt_pk_bf16_f32 v3, v6, v7
	v_lshlrev_b32_e32 v6, 16, v74
	v_and_b32_e32 v7, 0xffff0000, v74
	v_pk_fma_f32 v[26:27], v[22:23], v[26:27], v[30:31]
	v_lshlrev_b32_e32 v8, 16, v67
	v_pk_fma_f32 v[6:7], v[18:19], v[6:7], v[26:27] op_sel_hi:[0,1,1]
	v_lshlrev_b32_e32 v26, 16, v71
	v_and_b32_e32 v9, 0xffff0000, v71
	v_and_b32_e32 v27, 0xffff0000, v67
	v_pk_mul_f32 v[8:9], v[22:23], v[8:9] op_sel:[1,0] op_sel_hi:[0,1]
	v_cvt_pk_bf16_f32 v4, v6, v7
	v_lshlrev_b32_e32 v6, 16, v75
	v_and_b32_e32 v7, 0xffff0000, v75
	v_pk_fma_f32 v[8:9], v[22:23], v[26:27], v[8:9]
	s_nop 0
	v_pk_fma_f32 v[6:7], v[18:19], v[6:7], v[8:9] op_sel_hi:[0,1,1]
	v_cvt_pk_bf16_f32 v5, v6, v7
	global_store_dwordx4 v[20:21], v[2:5], off offset:2592
	v_lshlrev_b32_e32 v34, 16, v76
	v_and_b32_e32 v35, 0xffff0000, v80
	v_lshlrev_b32_e32 v32, 16, v80
	v_and_b32_e32 v33, 0xffff0000, v76
	v_pk_mul_f32 v[34:35], v[22:23], v[34:35] op_sel:[1,0] op_sel_hi:[0,1]
	v_lshlrev_b32_e32 v30, 16, v84
	v_and_b32_e32 v31, 0xffff0000, v84
	v_pk_fma_f32 v[32:33], v[22:23], v[32:33], v[34:35]
	v_lshlrev_b32_e32 v6, 16, v77
	v_pk_fma_f32 v[30:31], v[18:19], v[30:31], v[32:33] op_sel_hi:[0,1,1]
	v_cvt_pk_bf16_f32 v2, v30, v31
	v_lshlrev_b32_e32 v30, 16, v81
	v_and_b32_e32 v7, 0xffff0000, v81
	v_and_b32_e32 v31, 0xffff0000, v77
	v_pk_mul_f32 v[6:7], v[22:23], v[6:7] op_sel:[1,0] op_sel_hi:[0,1]
	v_lshlrev_b32_e32 v26, 16, v85
	v_and_b32_e32 v27, 0xffff0000, v85
	v_pk_fma_f32 v[6:7], v[22:23], v[30:31], v[6:7]
	v_lshlrev_b32_e32 v30, 16, v78
	v_and_b32_e32 v31, 0xffff0000, v82
	v_pk_fma_f32 v[6:7], v[18:19], v[26:27], v[6:7] op_sel_hi:[0,1,1]
	v_lshlrev_b32_e32 v26, 16, v82
	v_and_b32_e32 v27, 0xffff0000, v78
	v_pk_mul_f32 v[30:31], v[22:23], v[30:31] op_sel:[1,0] op_sel_hi:[0,1]
	v_cvt_pk_bf16_f32 v3, v6, v7
	v_lshlrev_b32_e32 v6, 16, v86
	v_and_b32_e32 v7, 0xffff0000, v86
	v_pk_fma_f32 v[26:27], v[22:23], v[26:27], v[30:31]
	v_lshlrev_b32_e32 v8, 16, v79
	v_pk_fma_f32 v[6:7], v[18:19], v[6:7], v[26:27] op_sel_hi:[0,1,1]
	v_lshlrev_b32_e32 v26, 16, v83
	v_and_b32_e32 v9, 0xffff0000, v83
	v_and_b32_e32 v27, 0xffff0000, v79
	v_pk_mul_f32 v[8:9], v[22:23], v[8:9] op_sel:[1,0] op_sel_hi:[0,1]
	v_cvt_pk_bf16_f32 v4, v6, v7
	v_lshlrev_b32_e32 v6, 16, v87
	v_and_b32_e32 v7, 0xffff0000, v87
	v_pk_fma_f32 v[8:9], v[22:23], v[26:27], v[8:9]
	s_nop 0
	v_pk_fma_f32 v[6:7], v[18:19], v[6:7], v[8:9] op_sel_hi:[0,1,1]
	v_cvt_pk_bf16_f32 v5, v6, v7
	global_store_dwordx4 v[20:21], v[2:5], off offset:2608
	v_lshlrev_b32_e32 v34, 16, v88
	v_and_b32_e32 v35, 0xffff0000, v92
	v_lshlrev_b32_e32 v32, 16, v92
	v_and_b32_e32 v33, 0xffff0000, v88
	v_pk_mul_f32 v[34:35], v[22:23], v[34:35] op_sel:[1,0] op_sel_hi:[0,1]
	v_lshlrev_b32_e32 v30, 16, v96
	v_and_b32_e32 v31, 0xffff0000, v96
	v_pk_fma_f32 v[32:33], v[22:23], v[32:33], v[34:35]
	v_lshlrev_b32_e32 v6, 16, v89
	v_pk_fma_f32 v[30:31], v[18:19], v[30:31], v[32:33] op_sel_hi:[0,1,1]
	v_cvt_pk_bf16_f32 v2, v30, v31
	v_lshlrev_b32_e32 v30, 16, v93
	v_and_b32_e32 v7, 0xffff0000, v93
	v_and_b32_e32 v31, 0xffff0000, v89
	v_pk_mul_f32 v[6:7], v[22:23], v[6:7] op_sel:[1,0] op_sel_hi:[0,1]
	v_lshlrev_b32_e32 v26, 16, v97
	v_and_b32_e32 v27, 0xffff0000, v97
	v_pk_fma_f32 v[6:7], v[22:23], v[30:31], v[6:7]
	v_lshlrev_b32_e32 v30, 16, v90
	v_and_b32_e32 v31, 0xffff0000, v94
	v_pk_fma_f32 v[6:7], v[18:19], v[26:27], v[6:7] op_sel_hi:[0,1,1]
	v_lshlrev_b32_e32 v26, 16, v94
	v_and_b32_e32 v27, 0xffff0000, v90
	v_pk_mul_f32 v[30:31], v[22:23], v[30:31] op_sel:[1,0] op_sel_hi:[0,1]
	v_cvt_pk_bf16_f32 v3, v6, v7
	v_lshlrev_b32_e32 v6, 16, v98
	v_and_b32_e32 v7, 0xffff0000, v98
	v_pk_fma_f32 v[26:27], v[22:23], v[26:27], v[30:31]
	v_lshlrev_b32_e32 v8, 16, v91
	v_pk_fma_f32 v[6:7], v[18:19], v[6:7], v[26:27] op_sel_hi:[0,1,1]
	v_lshlrev_b32_e32 v26, 16, v95
	v_and_b32_e32 v9, 0xffff0000, v95
	v_and_b32_e32 v27, 0xffff0000, v91
	v_pk_mul_f32 v[8:9], v[22:23], v[8:9] op_sel:[1,0] op_sel_hi:[0,1]
	v_cvt_pk_bf16_f32 v4, v6, v7
	v_lshlrev_b32_e32 v6, 16, v99
	v_and_b32_e32 v7, 0xffff0000, v99
	v_pk_fma_f32 v[8:9], v[22:23], v[26:27], v[8:9]
	s_nop 0
	v_pk_fma_f32 v[6:7], v[18:19], v[6:7], v[8:9] op_sel_hi:[0,1,1]
	v_cvt_pk_bf16_f32 v5, v6, v7
	global_store_dwordx4 v[20:21], v[2:5], off offset:2624
	v_lshlrev_b32_e32 v34, 16, v100
	v_and_b32_e32 v35, 0xffff0000, v104
	v_lshlrev_b32_e32 v32, 16, v104
	v_and_b32_e32 v33, 0xffff0000, v100
	v_pk_mul_f32 v[34:35], v[22:23], v[34:35] op_sel:[1,0] op_sel_hi:[0,1]
	v_lshlrev_b32_e32 v30, 16, v108
	v_and_b32_e32 v31, 0xffff0000, v108
	v_pk_fma_f32 v[32:33], v[22:23], v[32:33], v[34:35]
	v_lshlrev_b32_e32 v6, 16, v101
	v_pk_fma_f32 v[30:31], v[18:19], v[30:31], v[32:33] op_sel_hi:[0,1,1]
	v_cvt_pk_bf16_f32 v2, v30, v31
	v_lshlrev_b32_e32 v30, 16, v105
	v_and_b32_e32 v7, 0xffff0000, v105
	v_and_b32_e32 v31, 0xffff0000, v101
	v_pk_mul_f32 v[6:7], v[22:23], v[6:7] op_sel:[1,0] op_sel_hi:[0,1]
	v_lshlrev_b32_e32 v26, 16, v109
	v_and_b32_e32 v27, 0xffff0000, v109
	v_pk_fma_f32 v[6:7], v[22:23], v[30:31], v[6:7]
	v_lshlrev_b32_e32 v30, 16, v102
	v_and_b32_e32 v31, 0xffff0000, v106
	v_pk_fma_f32 v[6:7], v[18:19], v[26:27], v[6:7] op_sel_hi:[0,1,1]
	v_lshlrev_b32_e32 v26, 16, v106
	v_and_b32_e32 v27, 0xffff0000, v102
	v_pk_mul_f32 v[30:31], v[22:23], v[30:31] op_sel:[1,0] op_sel_hi:[0,1]
	v_cvt_pk_bf16_f32 v3, v6, v7
	v_lshlrev_b32_e32 v6, 16, v110
	v_and_b32_e32 v7, 0xffff0000, v110
	v_pk_fma_f32 v[26:27], v[22:23], v[26:27], v[30:31]
	v_lshlrev_b32_e32 v8, 16, v103
	v_pk_fma_f32 v[6:7], v[18:19], v[6:7], v[26:27] op_sel_hi:[0,1,1]
	v_lshlrev_b32_e32 v26, 16, v107
	v_and_b32_e32 v9, 0xffff0000, v107
	v_and_b32_e32 v27, 0xffff0000, v103
	v_pk_mul_f32 v[8:9], v[22:23], v[8:9] op_sel:[1,0] op_sel_hi:[0,1]
	v_cvt_pk_bf16_f32 v4, v6, v7
	v_lshlrev_b32_e32 v6, 16, v111
	v_and_b32_e32 v7, 0xffff0000, v111
	v_pk_fma_f32 v[8:9], v[22:23], v[26:27], v[8:9]
	s_nop 0
	v_pk_fma_f32 v[6:7], v[18:19], v[6:7], v[8:9] op_sel_hi:[0,1,1]
	v_cvt_pk_bf16_f32 v5, v6, v7
	global_store_dwordx4 v[20:21], v[2:5], off offset:2640
	v_lshlrev_b32_e32 v34, 16, v112
	v_and_b32_e32 v35, 0xffff0000, v116
	v_lshlrev_b32_e32 v32, 16, v116
	v_and_b32_e32 v33, 0xffff0000, v112
	v_pk_mul_f32 v[34:35], v[22:23], v[34:35] op_sel:[1,0] op_sel_hi:[0,1]
	v_lshlrev_b32_e32 v30, 16, v124
	v_and_b32_e32 v31, 0xffff0000, v124
	v_pk_fma_f32 v[32:33], v[22:23], v[32:33], v[34:35]
	v_lshlrev_b32_e32 v6, 16, v113
	v_pk_fma_f32 v[30:31], v[18:19], v[30:31], v[32:33] op_sel_hi:[0,1,1]
	v_cvt_pk_bf16_f32 v2, v30, v31
	v_lshlrev_b32_e32 v30, 16, v117
	v_and_b32_e32 v7, 0xffff0000, v117
	v_and_b32_e32 v31, 0xffff0000, v113
	v_pk_mul_f32 v[6:7], v[22:23], v[6:7] op_sel:[1,0] op_sel_hi:[0,1]
	v_lshlrev_b32_e32 v26, 16, v125
	v_and_b32_e32 v27, 0xffff0000, v125
	v_pk_fma_f32 v[6:7], v[22:23], v[30:31], v[6:7]
	v_lshlrev_b32_e32 v30, 16, v114
	v_and_b32_e32 v31, 0xffff0000, v118
	v_pk_fma_f32 v[6:7], v[18:19], v[26:27], v[6:7] op_sel_hi:[0,1,1]
	v_lshlrev_b32_e32 v26, 16, v118
	v_and_b32_e32 v27, 0xffff0000, v114
	v_pk_mul_f32 v[30:31], v[22:23], v[30:31] op_sel:[1,0] op_sel_hi:[0,1]
	v_cvt_pk_bf16_f32 v3, v6, v7
	v_lshlrev_b32_e32 v6, 16, v126
	v_and_b32_e32 v7, 0xffff0000, v126
	v_pk_fma_f32 v[26:27], v[22:23], v[26:27], v[30:31]
	v_lshlrev_b32_e32 v8, 16, v115
	v_pk_fma_f32 v[6:7], v[18:19], v[6:7], v[26:27] op_sel_hi:[0,1,1]
	v_lshlrev_b32_e32 v26, 16, v119
	v_and_b32_e32 v9, 0xffff0000, v119
	v_and_b32_e32 v27, 0xffff0000, v115
	v_pk_mul_f32 v[8:9], v[22:23], v[8:9] op_sel:[1,0] op_sel_hi:[0,1]
	v_cvt_pk_bf16_f32 v4, v6, v7
	v_lshlrev_b32_e32 v6, 16, v127
	v_and_b32_e32 v7, 0xffff0000, v127
	v_pk_fma_f32 v[8:9], v[22:23], v[26:27], v[8:9]
	s_nop 0
	v_pk_fma_f32 v[6:7], v[18:19], v[6:7], v[8:9] op_sel_hi:[0,1,1]
	v_cvt_pk_bf16_f32 v5, v6, v7
	global_store_dwordx4 v[20:21], v[2:5], off offset:2656
	v_lshlrev_b32_e32 v32, 16, v128
	v_and_b32_e32 v33, 0xffff0000, v132
	v_lshlrev_b32_e32 v30, 16, v132
	v_and_b32_e32 v31, 0xffff0000, v128
	v_pk_mul_f32 v[32:33], v[22:23], v[32:33] op_sel:[1,0] op_sel_hi:[0,1]
	v_lshlrev_b32_e32 v28, 16, v136
	v_and_b32_e32 v29, 0xffff0000, v136
	v_pk_fma_f32 v[30:31], v[22:23], v[30:31], v[32:33]
	v_lshlrev_b32_e32 v6, 16, v129
	v_pk_fma_f32 v[28:29], v[18:19], v[28:29], v[30:31] op_sel_hi:[0,1,1]
	v_cvt_pk_bf16_f32 v2, v28, v29
	v_lshlrev_b32_e32 v28, 16, v133
	v_and_b32_e32 v7, 0xffff0000, v133
	v_and_b32_e32 v29, 0xffff0000, v129
	v_pk_mul_f32 v[6:7], v[22:23], v[6:7] op_sel:[1,0] op_sel_hi:[0,1]
	v_lshlrev_b32_e32 v24, 16, v137
	v_and_b32_e32 v25, 0xffff0000, v137
	v_pk_fma_f32 v[6:7], v[22:23], v[28:29], v[6:7]
	v_lshlrev_b32_e32 v28, 16, v130
	v_and_b32_e32 v29, 0xffff0000, v134
	v_pk_fma_f32 v[6:7], v[18:19], v[24:25], v[6:7] op_sel_hi:[0,1,1]
	v_lshlrev_b32_e32 v24, 16, v134
	v_and_b32_e32 v25, 0xffff0000, v130
	v_pk_mul_f32 v[28:29], v[22:23], v[28:29] op_sel:[1,0] op_sel_hi:[0,1]
	v_cvt_pk_bf16_f32 v3, v6, v7
	v_lshlrev_b32_e32 v6, 16, v138
	v_and_b32_e32 v7, 0xffff0000, v138
	v_pk_fma_f32 v[24:25], v[22:23], v[24:25], v[28:29]
	v_lshlrev_b32_e32 v8, 16, v131
	v_pk_fma_f32 v[6:7], v[18:19], v[6:7], v[24:25] op_sel_hi:[0,1,1]
	v_lshlrev_b32_e32 v24, 16, v135
	v_and_b32_e32 v9, 0xffff0000, v135
	v_and_b32_e32 v25, 0xffff0000, v131
	v_pk_mul_f32 v[8:9], v[22:23], v[8:9] op_sel:[1,0] op_sel_hi:[0,1]
	v_cvt_pk_bf16_f32 v4, v6, v7
	v_lshlrev_b32_e32 v6, 16, v139
	v_and_b32_e32 v7, 0xffff0000, v139
	v_pk_fma_f32 v[8:9], v[22:23], v[24:25], v[8:9]
	s_nop 0
	v_pk_fma_f32 v[6:7], v[18:19], v[6:7], v[8:9] op_sel_hi:[0,1,1]
	v_cvt_pk_bf16_f32 v5, v6, v7
	global_store_dwordx4 v[20:21], v[2:5], off offset:2672
	global_load_dword v4, v[16:17], off offset:4
	s_nop 0
	v_or_b32_e32 v5, 1, v19
	v_lshlrev_b32_e32 v0, 2, v5
	v_lshl_add_u64 v[2:3], v[14:15], 0, v[0:1]
	global_load_dword v6, v[2:3], off
	v_lshl_add_u64 v[2:3], v[12:13], 0, v[0:1]
	global_load_dword v0, v[2:3], off
	s_waitcnt vmcnt(0) lgkmcnt(0)
	v_max3_f32 v7, v4, v6, v0
	v_sub_f32_e32 v2, v4, v7
	v_mul_f32_e32 v2, 0x3fb8aa3b, v2
	v_exp_f32_e32 v3, v2
	v_sub_f32_e32 v2, v6, v7
	v_mul_f32_e32 v2, 0x3fb8aa3b, v2
	v_sub_f32_e32 v0, v0, v7
	v_exp_f32_e32 v2, v2
	v_mul_f32_e32 v0, 0x3fb8aa3b, v0
	v_exp_f32_e32 v0, v0
	v_add_f32_e32 v4, v3, v2
	v_add_f32_e32 v4, v0, v4
	v_div_scale_f32 v6, s[4:5], v4, v4, 1.0
	v_rcp_f32_e32 v7, v6
	s_nop 0
	v_fma_f32 v8, -v6, v7, 1.0
	v_fmac_f32_e32 v7, v8, v7
	v_div_scale_f32 v8, vcc, 1.0, v4, 1.0
	v_mul_f32_e32 v9, v8, v7
	v_fma_f32 v12, -v6, v9, v8
	v_fmac_f32_e32 v9, v12, v7
	v_fma_f32 v6, -v6, v9, v8
	v_div_fmas_f32 v6, v6, v7, v9
	v_div_fixup_f32 v4, v6, v4, 1.0
	v_mul_f32_e32 v14, v0, v4
	v_lshlrev_b32_e32 v0, 7, v5
	v_lshl_add_u64 v[16:17], v[10:11], 0, v[0:1]
	global_load_dwordx4 v[40:43], v[16:17], off offset:2560
	global_load_dwordx4 v[44:47], v[16:17], off offset:3584
	v_add_co_u32_e32 v10, vcc, s8, v16
	v_pk_mul_f32 v[18:19], v[2:3], v[4:5] op_sel_hi:[1,0]
	s_nop 0
	v_addc_co_u32_e32 v11, vcc, 0, v17, vcc
	global_load_dwordx4 v[48:51], v[10:11], off
	global_load_dwordx4 v[52:55], v[16:17], off offset:2576
	s_nop 0
	global_load_dwordx4 v[56:59], v[16:17], off offset:3600
	global_load_dwordx4 v[60:63], v[10:11], off offset:16
	global_load_dwordx4 v[64:67], v[16:17], off offset:2592
	s_nop 0
	global_load_dwordx4 v[68:71], v[16:17], off offset:3616
	global_load_dwordx4 v[72:75], v[10:11], off offset:32
	global_load_dwordx4 v[76:79], v[16:17], off offset:2608
	s_nop 0
	global_load_dwordx4 v[80:83], v[16:17], off offset:3632
	global_load_dwordx4 v[84:87], v[10:11], off offset:48
	global_load_dwordx4 v[88:91], v[16:17], off offset:2624
	s_nop 0
	global_load_dwordx4 v[92:95], v[16:17], off offset:3648
	global_load_dwordx4 v[96:99], v[10:11], off offset:64
	global_load_dwordx4 v[100:103], v[16:17], off offset:2640
	s_nop 0
	global_load_dwordx4 v[104:107], v[16:17], off offset:3664
	global_load_dwordx4 v[108:111], v[10:11], off offset:80
	global_load_dwordx4 v[112:115], v[16:17], off offset:2656
	s_nop 0
	global_load_dwordx4 v[116:119], v[16:17], off offset:3680
	global_load_dwordx4 v[124:127], v[10:11], off offset:96
	global_load_dwordx4 v[128:131], v[16:17], off offset:2672
	s_nop 0
	global_load_dwordx4 v[132:135], v[16:17], off offset:3696
	s_nop 0
	global_load_dwordx4 v[136:139], v[10:11], off offset:112
	s_waitcnt vmcnt(0) lgkmcnt(0)
	v_lshlrev_b32_e32 v4, 16, v40
	v_and_b32_e32 v5, 0xffff0000, v44
	v_lshlrev_b32_e32 v2, 16, v44
	v_and_b32_e32 v3, 0xffff0000, v40
	v_pk_mul_f32 v[4:5], v[18:19], v[4:5] op_sel:[1,0] op_sel_hi:[0,1]
	v_pk_fma_f32 v[2:3], v[18:19], v[2:3], v[4:5]
	v_and_b32_e32 v5, 0xffff0000, v41
	v_lshlrev_b32_e32 v6, 16, v41
	v_and_b32_e32 v7, 0xffff0000, v45
	v_lshlrev_b32_e32 v4, 16, v45
	v_pk_mul_f32 v[6:7], v[18:19], v[6:7] op_sel:[1,0] op_sel_hi:[0,1]
	v_lshlrev_b32_e32 v12, 16, v48
	v_and_b32_e32 v13, 0xffff0000, v48
	v_lshlrev_b32_e32 v24, 16, v49
	v_and_b32_e32 v25, 0xffff0000, v49
	v_pk_fma_f32 v[4:5], v[18:19], v[4:5], v[6:7]
	v_pk_fma_f32 v[2:3], v[14:15], v[12:13], v[2:3] op_sel_hi:[0,1,1]
	v_pk_fma_f32 v[4:5], v[14:15], v[24:25], v[4:5] op_sel_hi:[0,1,1]
	v_lshlrev_b32_e32 v6, 16, v42
	v_and_b32_e32 v7, 0xffff0000, v46
	v_cvt_pk_bf16_f32 v2, v2, v3
	v_cvt_pk_bf16_f32 v3, v4, v5
	v_lshlrev_b32_e32 v4, 16, v46
	v_and_b32_e32 v5, 0xffff0000, v42
	v_pk_mul_f32 v[6:7], v[18:19], v[6:7] op_sel:[1,0] op_sel_hi:[0,1]
	v_pk_fma_f32 v[4:5], v[18:19], v[4:5], v[6:7]
	v_and_b32_e32 v7, 0xffff0000, v43
	v_lshlrev_b32_e32 v8, 16, v43
	v_and_b32_e32 v9, 0xffff0000, v47
	v_lshlrev_b32_e32 v6, 16, v47
	v_pk_mul_f32 v[8:9], v[18:19], v[8:9] op_sel:[1,0] op_sel_hi:[0,1]
	v_lshlrev_b32_e32 v28, 16, v50
	v_and_b32_e32 v29, 0xffff0000, v50
	v_lshlrev_b32_e32 v26, 16, v51
	v_and_b32_e32 v27, 0xffff0000, v51
	v_pk_fma_f32 v[6:7], v[18:19], v[6:7], v[8:9]
	v_pk_fma_f32 v[4:5], v[14:15], v[28:29], v[4:5] op_sel_hi:[0,1,1]
	v_pk_fma_f32 v[6:7], v[14:15], v[26:27], v[6:7] op_sel_hi:[0,1,1]
	v_cvt_pk_bf16_f32 v4, v4, v5
	v_cvt_pk_bf16_f32 v5, v6, v7
	global_store_dwordx4 v[16:17], v[2:5], off offset:2560
	v_lshlrev_b32_e32 v26, 16, v52
	v_and_b32_e32 v27, 0xffff0000, v56
	v_lshlrev_b32_e32 v24, 16, v56
	v_and_b32_e32 v25, 0xffff0000, v52
	v_pk_mul_f32 v[26:27], v[18:19], v[26:27] op_sel:[1,0] op_sel_hi:[0,1]
	v_lshlrev_b32_e32 v12, 16, v60
	v_and_b32_e32 v13, 0xffff0000, v60
	v_pk_fma_f32 v[24:25], v[18:19], v[24:25], v[26:27]
	v_lshlrev_b32_e32 v20, 16, v57
	v_pk_fma_f32 v[12:13], v[14:15], v[12:13], v[24:25] op_sel_hi:[0,1,1]
	v_lshlrev_b32_e32 v6, 16, v53
	v_and_b32_e32 v7, 0xffff0000, v57
	v_cvt_pk_bf16_f32 v2, v12, v13
	v_lshlrev_b32_e32 v12, 16, v61
	v_and_b32_e32 v13, 0xffff0000, v61
	v_and_b32_e32 v21, 0xffff0000, v53
	v_pk_mul_f32 v[6:7], v[18:19], v[6:7] op_sel:[1,0] op_sel_hi:[0,1]
	v_pk_fma_f32 v[6:7], v[18:19], v[20:21], v[6:7]
	v_lshlrev_b32_e32 v20, 16, v54
	v_and_b32_e32 v21, 0xffff0000, v58
	v_pk_fma_f32 v[6:7], v[14:15], v[12:13], v[6:7] op_sel_hi:[0,1,1]
	v_lshlrev_b32_e32 v12, 16, v58
	v_and_b32_e32 v13, 0xffff0000, v54
	v_pk_mul_f32 v[20:21], v[18:19], v[20:21] op_sel:[1,0] op_sel_hi:[0,1]
	v_cvt_pk_bf16_f32 v3, v6, v7
	v_lshlrev_b32_e32 v6, 16, v62
	v_and_b32_e32 v7, 0xffff0000, v62
	v_pk_fma_f32 v[12:13], v[18:19], v[12:13], v[20:21]
	v_lshlrev_b32_e32 v8, 16, v55
	v_pk_fma_f32 v[6:7], v[14:15], v[6:7], v[12:13] op_sel_hi:[0,1,1]
	v_lshlrev_b32_e32 v12, 16, v59
	v_and_b32_e32 v9, 0xffff0000, v59
	v_and_b32_e32 v13, 0xffff0000, v55
	v_pk_mul_f32 v[8:9], v[18:19], v[8:9] op_sel:[1,0] op_sel_hi:[0,1]
	v_cvt_pk_bf16_f32 v4, v6, v7
	v_lshlrev_b32_e32 v6, 16, v63
	v_and_b32_e32 v7, 0xffff0000, v63
	v_pk_fma_f32 v[8:9], v[18:19], v[12:13], v[8:9]
	s_nop 0
	v_pk_fma_f32 v[6:7], v[14:15], v[6:7], v[8:9] op_sel_hi:[0,1,1]
	v_cvt_pk_bf16_f32 v5, v6, v7
	global_store_dwordx4 v[16:17], v[2:5], off offset:2576
	v_lshlrev_b32_e32 v26, 16, v64
	v_and_b32_e32 v27, 0xffff0000, v68
	v_lshlrev_b32_e32 v24, 16, v68
	v_and_b32_e32 v25, 0xffff0000, v64
	v_pk_mul_f32 v[26:27], v[18:19], v[26:27] op_sel:[1,0] op_sel_hi:[0,1]
	v_lshlrev_b32_e32 v12, 16, v72
	v_and_b32_e32 v13, 0xffff0000, v72
	v_pk_fma_f32 v[24:25], v[18:19], v[24:25], v[26:27]
	v_lshlrev_b32_e32 v20, 16, v69
	v_pk_fma_f32 v[12:13], v[14:15], v[12:13], v[24:25] op_sel_hi:[0,1,1]
	v_lshlrev_b32_e32 v6, 16, v65
	v_and_b32_e32 v7, 0xffff0000, v69
	v_cvt_pk_bf16_f32 v2, v12, v13
	v_lshlrev_b32_e32 v12, 16, v73
	v_and_b32_e32 v13, 0xffff0000, v73
	v_and_b32_e32 v21, 0xffff0000, v65
	v_pk_mul_f32 v[6:7], v[18:19], v[6:7] op_sel:[1,0] op_sel_hi:[0,1]
	v_pk_fma_f32 v[6:7], v[18:19], v[20:21], v[6:7]
	v_lshlrev_b32_e32 v20, 16, v66
	v_and_b32_e32 v21, 0xffff0000, v70
	v_pk_fma_f32 v[6:7], v[14:15], v[12:13], v[6:7] op_sel_hi:[0,1,1]
	v_lshlrev_b32_e32 v12, 16, v70
	v_and_b32_e32 v13, 0xffff0000, v66
	v_pk_mul_f32 v[20:21], v[18:19], v[20:21] op_sel:[1,0] op_sel_hi:[0,1]
	v_cvt_pk_bf16_f32 v3, v6, v7
	v_lshlrev_b32_e32 v6, 16, v74
	v_and_b32_e32 v7, 0xffff0000, v74
	v_pk_fma_f32 v[12:13], v[18:19], v[12:13], v[20:21]
	v_lshlrev_b32_e32 v8, 16, v67
	v_pk_fma_f32 v[6:7], v[14:15], v[6:7], v[12:13] op_sel_hi:[0,1,1]
	v_lshlrev_b32_e32 v12, 16, v71
	v_and_b32_e32 v9, 0xffff0000, v71
	v_and_b32_e32 v13, 0xffff0000, v67
	v_pk_mul_f32 v[8:9], v[18:19], v[8:9] op_sel:[1,0] op_sel_hi:[0,1]
	v_cvt_pk_bf16_f32 v4, v6, v7
	v_lshlrev_b32_e32 v6, 16, v75
	v_and_b32_e32 v7, 0xffff0000, v75
	v_pk_fma_f32 v[8:9], v[18:19], v[12:13], v[8:9]
	s_nop 0
	v_pk_fma_f32 v[6:7], v[14:15], v[6:7], v[8:9] op_sel_hi:[0,1,1]
	v_cvt_pk_bf16_f32 v5, v6, v7
	global_store_dwordx4 v[16:17], v[2:5], off offset:2592
	v_lshlrev_b32_e32 v26, 16, v76
	v_and_b32_e32 v27, 0xffff0000, v80
	v_lshlrev_b32_e32 v24, 16, v80
	v_and_b32_e32 v25, 0xffff0000, v76
	v_pk_mul_f32 v[26:27], v[18:19], v[26:27] op_sel:[1,0] op_sel_hi:[0,1]
	v_lshlrev_b32_e32 v12, 16, v84
	v_and_b32_e32 v13, 0xffff0000, v84
	v_pk_fma_f32 v[24:25], v[18:19], v[24:25], v[26:27]
	v_lshlrev_b32_e32 v20, 16, v81
	v_pk_fma_f32 v[12:13], v[14:15], v[12:13], v[24:25] op_sel_hi:[0,1,1]
	v_lshlrev_b32_e32 v6, 16, v77
	v_and_b32_e32 v7, 0xffff0000, v81
	v_cvt_pk_bf16_f32 v2, v12, v13
	v_lshlrev_b32_e32 v12, 16, v85
	v_and_b32_e32 v13, 0xffff0000, v85
	v_and_b32_e32 v21, 0xffff0000, v77
	v_pk_mul_f32 v[6:7], v[18:19], v[6:7] op_sel:[1,0] op_sel_hi:[0,1]
	v_pk_fma_f32 v[6:7], v[18:19], v[20:21], v[6:7]
	v_lshlrev_b32_e32 v20, 16, v78
	v_and_b32_e32 v21, 0xffff0000, v82
	v_pk_fma_f32 v[6:7], v[14:15], v[12:13], v[6:7] op_sel_hi:[0,1,1]
	v_lshlrev_b32_e32 v12, 16, v82
	v_and_b32_e32 v13, 0xffff0000, v78
	v_pk_mul_f32 v[20:21], v[18:19], v[20:21] op_sel:[1,0] op_sel_hi:[0,1]
	v_cvt_pk_bf16_f32 v3, v6, v7
	v_lshlrev_b32_e32 v6, 16, v86
	v_and_b32_e32 v7, 0xffff0000, v86
	v_pk_fma_f32 v[12:13], v[18:19], v[12:13], v[20:21]
	v_lshlrev_b32_e32 v8, 16, v79
	v_pk_fma_f32 v[6:7], v[14:15], v[6:7], v[12:13] op_sel_hi:[0,1,1]
	v_lshlrev_b32_e32 v12, 16, v83
	v_and_b32_e32 v9, 0xffff0000, v83
	v_and_b32_e32 v13, 0xffff0000, v79
	v_pk_mul_f32 v[8:9], v[18:19], v[8:9] op_sel:[1,0] op_sel_hi:[0,1]
	v_cvt_pk_bf16_f32 v4, v6, v7
	v_lshlrev_b32_e32 v6, 16, v87
	v_and_b32_e32 v7, 0xffff0000, v87
	v_pk_fma_f32 v[8:9], v[18:19], v[12:13], v[8:9]
	s_nop 0
	v_pk_fma_f32 v[6:7], v[14:15], v[6:7], v[8:9] op_sel_hi:[0,1,1]
	v_cvt_pk_bf16_f32 v5, v6, v7
	global_store_dwordx4 v[16:17], v[2:5], off offset:2608
	v_lshlrev_b32_e32 v26, 16, v88
	v_and_b32_e32 v27, 0xffff0000, v92
	v_lshlrev_b32_e32 v24, 16, v92
	v_and_b32_e32 v25, 0xffff0000, v88
	v_pk_mul_f32 v[26:27], v[18:19], v[26:27] op_sel:[1,0] op_sel_hi:[0,1]
	v_lshlrev_b32_e32 v12, 16, v96
	v_and_b32_e32 v13, 0xffff0000, v96
	v_pk_fma_f32 v[24:25], v[18:19], v[24:25], v[26:27]
	v_lshlrev_b32_e32 v20, 16, v93
	v_pk_fma_f32 v[12:13], v[14:15], v[12:13], v[24:25] op_sel_hi:[0,1,1]
	v_lshlrev_b32_e32 v6, 16, v89
	v_and_b32_e32 v7, 0xffff0000, v93
	v_cvt_pk_bf16_f32 v2, v12, v13
	v_lshlrev_b32_e32 v12, 16, v97
	v_and_b32_e32 v13, 0xffff0000, v97
	v_and_b32_e32 v21, 0xffff0000, v89
	v_pk_mul_f32 v[6:7], v[18:19], v[6:7] op_sel:[1,0] op_sel_hi:[0,1]
	v_pk_fma_f32 v[6:7], v[18:19], v[20:21], v[6:7]
	v_lshlrev_b32_e32 v20, 16, v90
	v_and_b32_e32 v21, 0xffff0000, v94
	v_pk_fma_f32 v[6:7], v[14:15], v[12:13], v[6:7] op_sel_hi:[0,1,1]
	v_lshlrev_b32_e32 v12, 16, v94
	v_and_b32_e32 v13, 0xffff0000, v90
	v_pk_mul_f32 v[20:21], v[18:19], v[20:21] op_sel:[1,0] op_sel_hi:[0,1]
	v_cvt_pk_bf16_f32 v3, v6, v7
	v_lshlrev_b32_e32 v6, 16, v98
	v_and_b32_e32 v7, 0xffff0000, v98
	v_pk_fma_f32 v[12:13], v[18:19], v[12:13], v[20:21]
	v_lshlrev_b32_e32 v8, 16, v91
	v_pk_fma_f32 v[6:7], v[14:15], v[6:7], v[12:13] op_sel_hi:[0,1,1]
	v_lshlrev_b32_e32 v12, 16, v95
	v_and_b32_e32 v9, 0xffff0000, v95
	v_and_b32_e32 v13, 0xffff0000, v91
	v_pk_mul_f32 v[8:9], v[18:19], v[8:9] op_sel:[1,0] op_sel_hi:[0,1]
	v_cvt_pk_bf16_f32 v4, v6, v7
	v_lshlrev_b32_e32 v6, 16, v99
	v_and_b32_e32 v7, 0xffff0000, v99
	v_pk_fma_f32 v[8:9], v[18:19], v[12:13], v[8:9]
	s_nop 0
	v_pk_fma_f32 v[6:7], v[14:15], v[6:7], v[8:9] op_sel_hi:[0,1,1]
	v_cvt_pk_bf16_f32 v5, v6, v7
	global_store_dwordx4 v[16:17], v[2:5], off offset:2624
	v_lshlrev_b32_e32 v26, 16, v100
	v_and_b32_e32 v27, 0xffff0000, v104
	v_lshlrev_b32_e32 v24, 16, v104
	v_and_b32_e32 v25, 0xffff0000, v100
	v_pk_mul_f32 v[26:27], v[18:19], v[26:27] op_sel:[1,0] op_sel_hi:[0,1]
	v_lshlrev_b32_e32 v12, 16, v108
	v_and_b32_e32 v13, 0xffff0000, v108
	v_pk_fma_f32 v[24:25], v[18:19], v[24:25], v[26:27]
	v_lshlrev_b32_e32 v20, 16, v105
	v_pk_fma_f32 v[12:13], v[14:15], v[12:13], v[24:25] op_sel_hi:[0,1,1]
	v_lshlrev_b32_e32 v6, 16, v101
	v_and_b32_e32 v7, 0xffff0000, v105
	v_cvt_pk_bf16_f32 v2, v12, v13
	v_lshlrev_b32_e32 v12, 16, v109
	v_and_b32_e32 v13, 0xffff0000, v109
	v_and_b32_e32 v21, 0xffff0000, v101
	v_pk_mul_f32 v[6:7], v[18:19], v[6:7] op_sel:[1,0] op_sel_hi:[0,1]
	v_pk_fma_f32 v[6:7], v[18:19], v[20:21], v[6:7]
	v_lshlrev_b32_e32 v20, 16, v102
	v_and_b32_e32 v21, 0xffff0000, v106
	v_pk_fma_f32 v[6:7], v[14:15], v[12:13], v[6:7] op_sel_hi:[0,1,1]
	v_lshlrev_b32_e32 v12, 16, v106
	v_and_b32_e32 v13, 0xffff0000, v102
	v_pk_mul_f32 v[20:21], v[18:19], v[20:21] op_sel:[1,0] op_sel_hi:[0,1]
	v_cvt_pk_bf16_f32 v3, v6, v7
	v_lshlrev_b32_e32 v6, 16, v110
	v_and_b32_e32 v7, 0xffff0000, v110
	v_pk_fma_f32 v[12:13], v[18:19], v[12:13], v[20:21]
	v_lshlrev_b32_e32 v8, 16, v103
	v_pk_fma_f32 v[6:7], v[14:15], v[6:7], v[12:13] op_sel_hi:[0,1,1]
	v_lshlrev_b32_e32 v12, 16, v107
	v_and_b32_e32 v9, 0xffff0000, v107
	v_and_b32_e32 v13, 0xffff0000, v103
	v_pk_mul_f32 v[8:9], v[18:19], v[8:9] op_sel:[1,0] op_sel_hi:[0,1]
	v_cvt_pk_bf16_f32 v4, v6, v7
	v_lshlrev_b32_e32 v6, 16, v111
	v_and_b32_e32 v7, 0xffff0000, v111
	v_pk_fma_f32 v[8:9], v[18:19], v[12:13], v[8:9]
	s_nop 0
	v_pk_fma_f32 v[6:7], v[14:15], v[6:7], v[8:9] op_sel_hi:[0,1,1]
	v_cvt_pk_bf16_f32 v5, v6, v7
	global_store_dwordx4 v[16:17], v[2:5], off offset:2640
	v_lshlrev_b32_e32 v26, 16, v112
	v_and_b32_e32 v27, 0xffff0000, v116
	v_lshlrev_b32_e32 v24, 16, v116
	v_and_b32_e32 v25, 0xffff0000, v112
	v_pk_mul_f32 v[26:27], v[18:19], v[26:27] op_sel:[1,0] op_sel_hi:[0,1]
	v_lshlrev_b32_e32 v12, 16, v124
	v_and_b32_e32 v13, 0xffff0000, v124
	v_pk_fma_f32 v[24:25], v[18:19], v[24:25], v[26:27]
	v_lshlrev_b32_e32 v20, 16, v117
	v_pk_fma_f32 v[12:13], v[14:15], v[12:13], v[24:25] op_sel_hi:[0,1,1]
	v_lshlrev_b32_e32 v6, 16, v113
	v_and_b32_e32 v7, 0xffff0000, v117
	v_cvt_pk_bf16_f32 v2, v12, v13
	v_lshlrev_b32_e32 v12, 16, v125
	v_and_b32_e32 v13, 0xffff0000, v125
	v_and_b32_e32 v21, 0xffff0000, v113
	v_pk_mul_f32 v[6:7], v[18:19], v[6:7] op_sel:[1,0] op_sel_hi:[0,1]
	v_pk_fma_f32 v[6:7], v[18:19], v[20:21], v[6:7]
	v_lshlrev_b32_e32 v20, 16, v114
	v_and_b32_e32 v21, 0xffff0000, v118
	v_pk_fma_f32 v[6:7], v[14:15], v[12:13], v[6:7] op_sel_hi:[0,1,1]
	v_lshlrev_b32_e32 v12, 16, v118
	v_and_b32_e32 v13, 0xffff0000, v114
	v_pk_mul_f32 v[20:21], v[18:19], v[20:21] op_sel:[1,0] op_sel_hi:[0,1]
	v_cvt_pk_bf16_f32 v3, v6, v7
	v_lshlrev_b32_e32 v6, 16, v126
	v_and_b32_e32 v7, 0xffff0000, v126
	v_pk_fma_f32 v[12:13], v[18:19], v[12:13], v[20:21]
	v_lshlrev_b32_e32 v8, 16, v115
	v_pk_fma_f32 v[6:7], v[14:15], v[6:7], v[12:13] op_sel_hi:[0,1,1]
	v_lshlrev_b32_e32 v12, 16, v119
	v_and_b32_e32 v9, 0xffff0000, v119
	v_and_b32_e32 v13, 0xffff0000, v115
	v_pk_mul_f32 v[8:9], v[18:19], v[8:9] op_sel:[1,0] op_sel_hi:[0,1]
	v_cvt_pk_bf16_f32 v4, v6, v7
	v_lshlrev_b32_e32 v6, 16, v127
	v_and_b32_e32 v7, 0xffff0000, v127
	v_pk_fma_f32 v[8:9], v[18:19], v[12:13], v[8:9]
	s_nop 0
	v_pk_fma_f32 v[6:7], v[14:15], v[6:7], v[8:9] op_sel_hi:[0,1,1]
	v_cvt_pk_bf16_f32 v5, v6, v7
	global_store_dwordx4 v[16:17], v[2:5], off offset:2656
	v_lshlrev_b32_e32 v24, 16, v128
	v_and_b32_e32 v25, 0xffff0000, v132
	v_lshlrev_b32_e32 v22, 16, v132
	v_and_b32_e32 v23, 0xffff0000, v128
	v_pk_mul_f32 v[24:25], v[18:19], v[24:25] op_sel:[1,0] op_sel_hi:[0,1]
	v_lshlrev_b32_e32 v20, 16, v136
	v_and_b32_e32 v21, 0xffff0000, v136
	v_pk_fma_f32 v[22:23], v[18:19], v[22:23], v[24:25]
	v_lshlrev_b32_e32 v6, 16, v129
	v_pk_fma_f32 v[20:21], v[14:15], v[20:21], v[22:23] op_sel_hi:[0,1,1]
	v_cvt_pk_bf16_f32 v2, v20, v21
	v_lshlrev_b32_e32 v20, 16, v133
	v_and_b32_e32 v7, 0xffff0000, v133
	v_and_b32_e32 v21, 0xffff0000, v129
	v_pk_mul_f32 v[6:7], v[18:19], v[6:7] op_sel:[1,0] op_sel_hi:[0,1]
	v_lshlrev_b32_e32 v10, 16, v137
	v_and_b32_e32 v11, 0xffff0000, v137
	v_pk_fma_f32 v[6:7], v[18:19], v[20:21], v[6:7]
	v_lshlrev_b32_e32 v20, 16, v130
	v_and_b32_e32 v21, 0xffff0000, v134
	v_pk_fma_f32 v[6:7], v[14:15], v[10:11], v[6:7] op_sel_hi:[0,1,1]
	v_lshlrev_b32_e32 v10, 16, v134
	v_and_b32_e32 v11, 0xffff0000, v130
	v_pk_mul_f32 v[20:21], v[18:19], v[20:21] op_sel:[1,0] op_sel_hi:[0,1]
	v_cvt_pk_bf16_f32 v3, v6, v7
	v_lshlrev_b32_e32 v6, 16, v138
	v_and_b32_e32 v7, 0xffff0000, v138
	v_pk_fma_f32 v[10:11], v[18:19], v[10:11], v[20:21]
	v_lshlrev_b32_e32 v8, 16, v131
	v_pk_fma_f32 v[6:7], v[14:15], v[6:7], v[10:11] op_sel_hi:[0,1,1]
	v_lshlrev_b32_e32 v10, 16, v135
	v_and_b32_e32 v9, 0xffff0000, v135
	v_and_b32_e32 v11, 0xffff0000, v131
	v_pk_mul_f32 v[8:9], v[18:19], v[8:9] op_sel:[1,0] op_sel_hi:[0,1]
	v_cvt_pk_bf16_f32 v4, v6, v7
	v_lshlrev_b32_e32 v6, 16, v139
	v_and_b32_e32 v7, 0xffff0000, v139
	v_pk_fma_f32 v[8:9], v[18:19], v[10:11], v[8:9]
	s_nop 0
	v_pk_fma_f32 v[6:7], v[14:15], v[6:7], v[8:9] op_sel_hi:[0,1,1]
	v_cvt_pk_bf16_f32 v5, v6, v7
	global_store_dwordx4 v[16:17], v[2:5], off offset:2672
